# UQ/UKV phase preamble: per tile slot the six load+wait iterations of the latent sum-of-squares replaced by 24 loads issued together and one wait
# speedup vs baseline: 1.0002x; 1.0002x over previous
; DI float bf2f(unsigned v) { return __uint_as_float(v << 16); }
; DI void rinv_prepass(const u16* __restrict__ A, int K, const pg8::StaticOrder& S, LAS float* tab) {
;     ...
;     const u16* pr = A + (size_t)(u.pm * 256 + row) * K + half * (K >> 1);
;     float ss = 0.f;
;     for (int c = 0; c < (K >> 1); c += 8) {
;       u32x4 w = *(const u32x4*)(pr + c);
;       float a;
;       a = bf2f(w.x & 0xffffu); ss += a * a; a = bf2f(w.x >> 16); ss += a * a;
;       a = bf2f(w.y & 0xffffu); ss += a * a; a = bf2f(w.y >> 16); ss += a * a;
;       a = bf2f(w.z & 0xffffu); ss += a * a; a = bf2f(w.z >> 16); ss += a * a;
;       a = bf2f(w.w & 0xffffu); ss += a * a; a = bf2f(w.w >> 16); ss += a * a;
;     }
.LBB0_1168:
	global_load_dwordx4 v[32:35], v[0:1], off offset:16
	global_load_dwordx4 v[36:39], v[0:1], off
	global_load_dwordx4 v[40:43], v[0:1], off offset:-16
	global_load_dwordx4 v[44:47], v[0:1], off offset:-32
	global_load_dwordx4 v[48:51], v[0:1], off offset:80
	global_load_dwordx4 v[52:55], v[0:1], off offset:64
	global_load_dwordx4 v[56:59], v[0:1], off offset:48
	global_load_dwordx4 v[60:63], v[0:1], off offset:32
	global_load_dwordx4 v[64:67], v[0:1], off offset:144
	global_load_dwordx4 v[68:71], v[0:1], off offset:128
	global_load_dwordx4 v[72:75], v[0:1], off offset:112
	global_load_dwordx4 v[76:79], v[0:1], off offset:96
	global_load_dwordx4 v[80:83], v[0:1], off offset:208
	global_load_dwordx4 v[84:87], v[0:1], off offset:192
	global_load_dwordx4 v[88:91], v[0:1], off offset:176
	global_load_dwordx4 v[92:95], v[0:1], off offset:160
	global_load_dwordx4 v[96:99], v[0:1], off offset:272
	global_load_dwordx4 v[100:103], v[0:1], off offset:256
	global_load_dwordx4 v[104:107], v[0:1], off offset:240
	global_load_dwordx4 v[108:111], v[0:1], off offset:224
	global_load_dwordx4 v[112:115], v[0:1], off offset:336
	global_load_dwordx4 v[116:119], v[0:1], off offset:320
	global_load_dwordx4 v[120:123], v[0:1], off offset:304
	global_load_dwordx4 v[124:127], v[0:1], off offset:288
	s_waitcnt vmcnt(0)
	v_lshlrev_b32_e32 v4, 16, v44
	v_lshlrev_b32_e32 v25, 16, v45
	v_and_b32_e32 v24, 0xffff0000, v44
	v_fmac_f32_e32 v6, v4, v4
	v_pk_mul_f32 v[24:25], v[24:25], v[24:25]
	v_lshlrev_b32_e32 v7, 16, v46
	v_add_f32_e32 v4, v24, v6
	v_and_b32_e32 v6, 0xffff0000, v45
	v_add_f32_e32 v4, v25, v4
	v_pk_mul_f32 v[6:7], v[6:7], v[6:7]
	s_nop 0
	v_add_f32_e32 v4, v6, v4
	v_add_f32_e32 v4, v7, v4
	v_lshlrev_b32_e32 v7, 16, v47
	v_and_b32_e32 v6, 0xffff0000, v46
	v_pk_mul_f32 v[6:7], v[6:7], v[6:7]
	s_nop 0
	v_add_f32_e32 v4, v6, v4
	v_add_f32_e32 v4, v7, v4
	v_and_b32_e32 v6, 0xffff0000, v47
	v_fmac_f32_e32 v4, v6, v6
	v_lshlrev_b32_e32 v6, 16, v40
	v_fmac_f32_e32 v4, v6, v6
	v_lshlrev_b32_e32 v7, 16, v41
	v_and_b32_e32 v6, 0xffff0000, v40
	v_pk_mul_f32 v[6:7], v[6:7], v[6:7]
	s_nop 0
	v_add_f32_e32 v4, v6, v4
	v_add_f32_e32 v4, v7, v4
	v_lshlrev_b32_e32 v7, 16, v42
	v_and_b32_e32 v6, 0xffff0000, v41
	v_pk_mul_f32 v[6:7], v[6:7], v[6:7]
	s_nop 0
	v_add_f32_e32 v4, v6, v4
	v_add_f32_e32 v4, v7, v4
	v_lshlrev_b32_e32 v7, 16, v43
	v_and_b32_e32 v6, 0xffff0000, v42
	v_pk_mul_f32 v[6:7], v[6:7], v[6:7]
	s_nop 0
	v_add_f32_e32 v4, v6, v4
	v_add_f32_e32 v4, v7, v4
	v_and_b32_e32 v6, 0xffff0000, v43
	v_fmac_f32_e32 v4, v6, v6
	v_lshlrev_b32_e32 v6, 16, v36
	v_fmac_f32_e32 v4, v6, v6
	v_lshlrev_b32_e32 v7, 16, v37
	v_and_b32_e32 v6, 0xffff0000, v36
	v_pk_mul_f32 v[6:7], v[6:7], v[6:7]
	s_nop 0
	v_add_f32_e32 v4, v6, v4
	v_add_f32_e32 v4, v7, v4
	v_lshlrev_b32_e32 v7, 16, v38
	v_and_b32_e32 v6, 0xffff0000, v37
	v_pk_mul_f32 v[6:7], v[6:7], v[6:7]
	s_nop 0
	v_add_f32_e32 v4, v6, v4
	v_add_f32_e32 v4, v7, v4
	v_lshlrev_b32_e32 v7, 16, v39
	v_and_b32_e32 v6, 0xffff0000, v38
	v_pk_mul_f32 v[6:7], v[6:7], v[6:7]
	s_nop 0
	v_add_f32_e32 v4, v6, v4
	v_add_f32_e32 v4, v7, v4
	v_and_b32_e32 v6, 0xffff0000, v39
	v_fmac_f32_e32 v4, v6, v6
	v_lshlrev_b32_e32 v6, 16, v32
	v_fmac_f32_e32 v4, v6, v6
	v_lshlrev_b32_e32 v7, 16, v33
	v_and_b32_e32 v6, 0xffff0000, v32
	v_pk_mul_f32 v[6:7], v[6:7], v[6:7]
	s_nop 0
	v_add_f32_e32 v4, v6, v4
	v_add_f32_e32 v4, v7, v4
	v_lshlrev_b32_e32 v7, 16, v34
	v_and_b32_e32 v6, 0xffff0000, v33
	v_pk_mul_f32 v[6:7], v[6:7], v[6:7]
	s_nop 0
	v_add_f32_e32 v4, v6, v4
	v_add_f32_e32 v4, v7, v4
	v_lshlrev_b32_e32 v7, 16, v35
	v_and_b32_e32 v6, 0xffff0000, v34
	v_pk_mul_f32 v[6:7], v[6:7], v[6:7]
	s_nop 0
	v_add_f32_e32 v4, v6, v4
	v_add_f32_e32 v6, v7, v4
	v_and_b32_e32 v4, 0xffff0000, v35
	v_fmac_f32_e32 v6, v4, v4
	v_lshlrev_b32_e32 v4, 16, v60
	v_lshlrev_b32_e32 v25, 16, v61
	v_and_b32_e32 v24, 0xffff0000, v60
	v_fmac_f32_e32 v6, v4, v4
	v_pk_mul_f32 v[24:25], v[24:25], v[24:25]
	v_lshlrev_b32_e32 v7, 16, v62
	v_add_f32_e32 v4, v24, v6
	v_and_b32_e32 v6, 0xffff0000, v61
	v_add_f32_e32 v4, v25, v4
	v_pk_mul_f32 v[6:7], v[6:7], v[6:7]
	s_nop 0
	v_add_f32_e32 v4, v6, v4
	v_add_f32_e32 v4, v7, v4
	v_lshlrev_b32_e32 v7, 16, v63
	v_and_b32_e32 v6, 0xffff0000, v62
	v_pk_mul_f32 v[6:7], v[6:7], v[6:7]
	s_nop 0
	v_add_f32_e32 v4, v6, v4
	v_add_f32_e32 v4, v7, v4
	v_and_b32_e32 v6, 0xffff0000, v63
	v_fmac_f32_e32 v4, v6, v6
	v_lshlrev_b32_e32 v6, 16, v56
	v_fmac_f32_e32 v4, v6, v6
	v_lshlrev_b32_e32 v7, 16, v57
	v_and_b32_e32 v6, 0xffff0000, v56
	v_pk_mul_f32 v[6:7], v[6:7], v[6:7]
	s_nop 0
	v_add_f32_e32 v4, v6, v4
	v_add_f32_e32 v4, v7, v4
	v_lshlrev_b32_e32 v7, 16, v58
	v_and_b32_e32 v6, 0xffff0000, v57
	v_pk_mul_f32 v[6:7], v[6:7], v[6:7]
	s_nop 0
	v_add_f32_e32 v4, v6, v4
	v_add_f32_e32 v4, v7, v4
	v_lshlrev_b32_e32 v7, 16, v59
	v_and_b32_e32 v6, 0xffff0000, v58
	v_pk_mul_f32 v[6:7], v[6:7], v[6:7]
	s_nop 0
	v_add_f32_e32 v4, v6, v4
	v_add_f32_e32 v4, v7, v4
	v_and_b32_e32 v6, 0xffff0000, v59
	v_fmac_f32_e32 v4, v6, v6
	v_lshlrev_b32_e32 v6, 16, v52
	v_fmac_f32_e32 v4, v6, v6
	v_lshlrev_b32_e32 v7, 16, v53
	v_and_b32_e32 v6, 0xffff0000, v52
	v_pk_mul_f32 v[6:7], v[6:7], v[6:7]
	s_nop 0
	v_add_f32_e32 v4, v6, v4
	v_add_f32_e32 v4, v7, v4
	v_lshlrev_b32_e32 v7, 16, v54
	v_and_b32_e32 v6, 0xffff0000, v53
	v_pk_mul_f32 v[6:7], v[6:7], v[6:7]
	s_nop 0
	v_add_f32_e32 v4, v6, v4
	v_add_f32_e32 v4, v7, v4
	v_lshlrev_b32_e32 v7, 16, v55
	v_and_b32_e32 v6, 0xffff0000, v54
	v_pk_mul_f32 v[6:7], v[6:7], v[6:7]
	s_nop 0
	v_add_f32_e32 v4, v6, v4
	v_add_f32_e32 v4, v7, v4
	v_and_b32_e32 v6, 0xffff0000, v55
	v_fmac_f32_e32 v4, v6, v6
	v_lshlrev_b32_e32 v6, 16, v48
; DI float bf2f(unsigned v) { return __uint_as_float(v << 16); }
; DI void rinv_prepass(const u16* __restrict__ A, int K, const pg8::StaticOrder& S, LAS float* tab) {
;     ...
;     for (int c = 0; c < (K >> 1); c += 8) {
;       u32x4 w = *(const u32x4*)(pr + c);
;       float a;
;       a = bf2f(w.x & 0xffffu); ss += a * a; a = bf2f(w.x >> 16); ss += a * a;
;       a = bf2f(w.y & 0xffffu); ss += a * a; a = bf2f(w.y >> 16); ss += a * a;
;       a = bf2f(w.z & 0xffffu); ss += a * a; a = bf2f(w.z >> 16); ss += a * a;
;       a = bf2f(w.w & 0xffffu); ss += a * a; a = bf2f(w.w >> 16); ss += a * a;
;     }
	v_fmac_f32_e32 v4, v6, v6
	v_lshlrev_b32_e32 v7, 16, v49
	v_and_b32_e32 v6, 0xffff0000, v48
	v_pk_mul_f32 v[6:7], v[6:7], v[6:7]
	s_nop 0
	v_add_f32_e32 v4, v6, v4
	v_add_f32_e32 v4, v7, v4
	v_lshlrev_b32_e32 v7, 16, v50
	v_and_b32_e32 v6, 0xffff0000, v49
	v_pk_mul_f32 v[6:7], v[6:7], v[6:7]
	s_nop 0
	v_add_f32_e32 v4, v6, v4
	v_add_f32_e32 v4, v7, v4
	v_lshlrev_b32_e32 v7, 16, v51
	v_and_b32_e32 v6, 0xffff0000, v50
	v_pk_mul_f32 v[6:7], v[6:7], v[6:7]
	s_nop 0
	v_add_f32_e32 v4, v6, v4
	v_add_f32_e32 v6, v7, v4
	v_and_b32_e32 v4, 0xffff0000, v51
	v_fmac_f32_e32 v6, v4, v4
	v_lshlrev_b32_e32 v4, 16, v76
	v_lshlrev_b32_e32 v25, 16, v77
	v_and_b32_e32 v24, 0xffff0000, v76
	v_fmac_f32_e32 v6, v4, v4
	v_pk_mul_f32 v[24:25], v[24:25], v[24:25]
	v_lshlrev_b32_e32 v7, 16, v78
	v_add_f32_e32 v4, v24, v6
	v_and_b32_e32 v6, 0xffff0000, v77
	v_add_f32_e32 v4, v25, v4
	v_pk_mul_f32 v[6:7], v[6:7], v[6:7]
	s_nop 0
	v_add_f32_e32 v4, v6, v4
	v_add_f32_e32 v4, v7, v4
	v_lshlrev_b32_e32 v7, 16, v79
	v_and_b32_e32 v6, 0xffff0000, v78
	v_pk_mul_f32 v[6:7], v[6:7], v[6:7]
	s_nop 0
	v_add_f32_e32 v4, v6, v4
	v_add_f32_e32 v4, v7, v4
	v_and_b32_e32 v6, 0xffff0000, v79
	v_fmac_f32_e32 v4, v6, v6
	v_lshlrev_b32_e32 v6, 16, v72
	v_fmac_f32_e32 v4, v6, v6
	v_lshlrev_b32_e32 v7, 16, v73
	v_and_b32_e32 v6, 0xffff0000, v72
	v_pk_mul_f32 v[6:7], v[6:7], v[6:7]
	s_nop 0
	v_add_f32_e32 v4, v6, v4
	v_add_f32_e32 v4, v7, v4
	v_lshlrev_b32_e32 v7, 16, v74
	v_and_b32_e32 v6, 0xffff0000, v73
	v_pk_mul_f32 v[6:7], v[6:7], v[6:7]
	s_nop 0
	v_add_f32_e32 v4, v6, v4
	v_add_f32_e32 v4, v7, v4
	v_lshlrev_b32_e32 v7, 16, v75
	v_and_b32_e32 v6, 0xffff0000, v74
	v_pk_mul_f32 v[6:7], v[6:7], v[6:7]
	s_nop 0
	v_add_f32_e32 v4, v6, v4
	v_add_f32_e32 v4, v7, v4
	v_and_b32_e32 v6, 0xffff0000, v75
	v_fmac_f32_e32 v4, v6, v6
	v_lshlrev_b32_e32 v6, 16, v68
	v_fmac_f32_e32 v4, v6, v6
	v_lshlrev_b32_e32 v7, 16, v69
	v_and_b32_e32 v6, 0xffff0000, v68
	v_pk_mul_f32 v[6:7], v[6:7], v[6:7]
	s_nop 0
	v_add_f32_e32 v4, v6, v4
	v_add_f32_e32 v4, v7, v4
	v_lshlrev_b32_e32 v7, 16, v70
	v_and_b32_e32 v6, 0xffff0000, v69
	v_pk_mul_f32 v[6:7], v[6:7], v[6:7]
	s_nop 0
	v_add_f32_e32 v4, v6, v4
	v_add_f32_e32 v4, v7, v4
	v_lshlrev_b32_e32 v7, 16, v71
	v_and_b32_e32 v6, 0xffff0000, v70
	v_pk_mul_f32 v[6:7], v[6:7], v[6:7]
	s_nop 0
	v_add_f32_e32 v4, v6, v4
	v_add_f32_e32 v4, v7, v4
	v_and_b32_e32 v6, 0xffff0000, v71
	v_fmac_f32_e32 v4, v6, v6
	v_lshlrev_b32_e32 v6, 16, v64
	v_fmac_f32_e32 v4, v6, v6
	v_lshlrev_b32_e32 v7, 16, v65
	v_and_b32_e32 v6, 0xffff0000, v64
	v_pk_mul_f32 v[6:7], v[6:7], v[6:7]
	s_nop 0
	v_add_f32_e32 v4, v6, v4
	v_add_f32_e32 v4, v7, v4
	v_lshlrev_b32_e32 v7, 16, v66
	v_and_b32_e32 v6, 0xffff0000, v65
	v_pk_mul_f32 v[6:7], v[6:7], v[6:7]
	s_nop 0
	v_add_f32_e32 v4, v6, v4
	v_add_f32_e32 v4, v7, v4
	v_lshlrev_b32_e32 v7, 16, v67
	v_and_b32_e32 v6, 0xffff0000, v66
	v_pk_mul_f32 v[6:7], v[6:7], v[6:7]
	s_nop 0
	v_add_f32_e32 v4, v6, v4
	v_add_f32_e32 v6, v7, v4
	v_and_b32_e32 v4, 0xffff0000, v67
	v_fmac_f32_e32 v6, v4, v4
	v_lshlrev_b32_e32 v4, 16, v92
	v_lshlrev_b32_e32 v25, 16, v93
	v_and_b32_e32 v24, 0xffff0000, v92
	v_fmac_f32_e32 v6, v4, v4
	v_pk_mul_f32 v[24:25], v[24:25], v[24:25]
	v_lshlrev_b32_e32 v7, 16, v94
	v_add_f32_e32 v4, v24, v6
	v_and_b32_e32 v6, 0xffff0000, v93
	v_add_f32_e32 v4, v25, v4
	v_pk_mul_f32 v[6:7], v[6:7], v[6:7]
	s_nop 0
	v_add_f32_e32 v4, v6, v4
	v_add_f32_e32 v4, v7, v4
	v_lshlrev_b32_e32 v7, 16, v95
	v_and_b32_e32 v6, 0xffff0000, v94
	v_pk_mul_f32 v[6:7], v[6:7], v[6:7]
	s_nop 0
	v_add_f32_e32 v4, v6, v4
	v_add_f32_e32 v4, v7, v4
	v_and_b32_e32 v6, 0xffff0000, v95
	v_fmac_f32_e32 v4, v6, v6
	v_lshlrev_b32_e32 v6, 16, v88
	v_fmac_f32_e32 v4, v6, v6
	v_lshlrev_b32_e32 v7, 16, v89
	v_and_b32_e32 v6, 0xffff0000, v88
	v_pk_mul_f32 v[6:7], v[6:7], v[6:7]
	s_nop 0
	v_add_f32_e32 v4, v6, v4
	v_add_f32_e32 v4, v7, v4
	v_lshlrev_b32_e32 v7, 16, v90
	v_and_b32_e32 v6, 0xffff0000, v89
	v_pk_mul_f32 v[6:7], v[6:7], v[6:7]
	s_nop 0
	v_add_f32_e32 v4, v6, v4
	v_add_f32_e32 v4, v7, v4
	v_lshlrev_b32_e32 v7, 16, v91
	v_and_b32_e32 v6, 0xffff0000, v90
	v_pk_mul_f32 v[6:7], v[6:7], v[6:7]
	s_nop 0
	v_add_f32_e32 v4, v6, v4
	v_add_f32_e32 v4, v7, v4
	v_and_b32_e32 v6, 0xffff0000, v91
	v_fmac_f32_e32 v4, v6, v6
	v_lshlrev_b32_e32 v6, 16, v84
	v_fmac_f32_e32 v4, v6, v6
	v_lshlrev_b32_e32 v7, 16, v85
	v_and_b32_e32 v6, 0xffff0000, v84
	v_pk_mul_f32 v[6:7], v[6:7], v[6:7]
	s_nop 0
	v_add_f32_e32 v4, v6, v4
	v_add_f32_e32 v4, v7, v4
	v_lshlrev_b32_e32 v7, 16, v86
	v_and_b32_e32 v6, 0xffff0000, v85
	v_pk_mul_f32 v[6:7], v[6:7], v[6:7]
	s_nop 0
	v_add_f32_e32 v4, v6, v4
	v_add_f32_e32 v4, v7, v4
	v_lshlrev_b32_e32 v7, 16, v87
	v_and_b32_e32 v6, 0xffff0000, v86
	v_pk_mul_f32 v[6:7], v[6:7], v[6:7]
	s_nop 0
	v_add_f32_e32 v4, v6, v4
	v_add_f32_e32 v4, v7, v4
	v_and_b32_e32 v6, 0xffff0000, v87
	v_fmac_f32_e32 v4, v6, v6
	v_lshlrev_b32_e32 v6, 16, v80
	v_fmac_f32_e32 v4, v6, v6
	v_lshlrev_b32_e32 v7, 16, v81
	v_and_b32_e32 v6, 0xffff0000, v80
	v_pk_mul_f32 v[6:7], v[6:7], v[6:7]
	s_nop 0
	v_add_f32_e32 v4, v6, v4
	v_add_f32_e32 v4, v7, v4
	v_lshlrev_b32_e32 v7, 16, v82
	v_and_b32_e32 v6, 0xffff0000, v81
	v_pk_mul_f32 v[6:7], v[6:7], v[6:7]
	s_nop 0
	v_add_f32_e32 v4, v6, v4
	v_add_f32_e32 v4, v7, v4
	v_lshlrev_b32_e32 v7, 16, v83
	v_and_b32_e32 v6, 0xffff0000, v82
	v_pk_mul_f32 v[6:7], v[6:7], v[6:7]
	s_nop 0
	v_add_f32_e32 v4, v6, v4
	v_add_f32_e32 v6, v7, v4
	v_and_b32_e32 v4, 0xffff0000, v83
	v_fmac_f32_e32 v6, v4, v4
	v_lshlrev_b32_e32 v4, 16, v108
	v_lshlrev_b32_e32 v25, 16, v109
	v_and_b32_e32 v24, 0xffff0000, v108
	v_fmac_f32_e32 v6, v4, v4
	v_pk_mul_f32 v[24:25], v[24:25], v[24:25]
; DI float bf2f(unsigned v) { return __uint_as_float(v << 16); }
; DI void rinv_prepass(const u16* __restrict__ A, int K, const pg8::StaticOrder& S, LAS float* tab) {
;     ...
;     for (int c = 0; c < (K >> 1); c += 8) {
;       u32x4 w = *(const u32x4*)(pr + c);
;       float a;
;       a = bf2f(w.x & 0xffffu); ss += a * a; a = bf2f(w.x >> 16); ss += a * a;
;       a = bf2f(w.y & 0xffffu); ss += a * a; a = bf2f(w.y >> 16); ss += a * a;
;       a = bf2f(w.z & 0xffffu); ss += a * a; a = bf2f(w.z >> 16); ss += a * a;
;       a = bf2f(w.w & 0xffffu); ss += a * a; a = bf2f(w.w >> 16); ss += a * a;
;     }
;     ss += shx(ss, 1, tid & 63);
;     if (!half) tab[i * 256 + row] = rsqrtf(ss / (float)K + EPS);
	v_lshlrev_b32_e32 v7, 16, v110
	v_add_f32_e32 v4, v24, v6
	v_and_b32_e32 v6, 0xffff0000, v109
	v_add_f32_e32 v4, v25, v4
	v_pk_mul_f32 v[6:7], v[6:7], v[6:7]
	s_nop 0
	v_add_f32_e32 v4, v6, v4
	v_add_f32_e32 v4, v7, v4
	v_lshlrev_b32_e32 v7, 16, v111
	v_and_b32_e32 v6, 0xffff0000, v110
	v_pk_mul_f32 v[6:7], v[6:7], v[6:7]
	s_nop 0
	v_add_f32_e32 v4, v6, v4
	v_add_f32_e32 v4, v7, v4
	v_and_b32_e32 v6, 0xffff0000, v111
	v_fmac_f32_e32 v4, v6, v6
	v_lshlrev_b32_e32 v6, 16, v104
	v_fmac_f32_e32 v4, v6, v6
	v_lshlrev_b32_e32 v7, 16, v105
	v_and_b32_e32 v6, 0xffff0000, v104
	v_pk_mul_f32 v[6:7], v[6:7], v[6:7]
	s_nop 0
	v_add_f32_e32 v4, v6, v4
	v_add_f32_e32 v4, v7, v4
	v_lshlrev_b32_e32 v7, 16, v106
	v_and_b32_e32 v6, 0xffff0000, v105
	v_pk_mul_f32 v[6:7], v[6:7], v[6:7]
	s_nop 0
	v_add_f32_e32 v4, v6, v4
	v_add_f32_e32 v4, v7, v4
	v_lshlrev_b32_e32 v7, 16, v107
	v_and_b32_e32 v6, 0xffff0000, v106
	v_pk_mul_f32 v[6:7], v[6:7], v[6:7]
	s_nop 0
	v_add_f32_e32 v4, v6, v4
	v_add_f32_e32 v4, v7, v4
	v_and_b32_e32 v6, 0xffff0000, v107
	v_fmac_f32_e32 v4, v6, v6
	v_lshlrev_b32_e32 v6, 16, v100
	v_fmac_f32_e32 v4, v6, v6
	v_lshlrev_b32_e32 v7, 16, v101
	v_and_b32_e32 v6, 0xffff0000, v100
	v_pk_mul_f32 v[6:7], v[6:7], v[6:7]
	s_nop 0
	v_add_f32_e32 v4, v6, v4
	v_add_f32_e32 v4, v7, v4
	v_lshlrev_b32_e32 v7, 16, v102
	v_and_b32_e32 v6, 0xffff0000, v101
	v_pk_mul_f32 v[6:7], v[6:7], v[6:7]
	s_nop 0
	v_add_f32_e32 v4, v6, v4
	v_add_f32_e32 v4, v7, v4
	v_lshlrev_b32_e32 v7, 16, v103
	v_and_b32_e32 v6, 0xffff0000, v102
	v_pk_mul_f32 v[6:7], v[6:7], v[6:7]
	s_nop 0
	v_add_f32_e32 v4, v6, v4
	v_add_f32_e32 v4, v7, v4
	v_and_b32_e32 v6, 0xffff0000, v103
	v_fmac_f32_e32 v4, v6, v6
	v_lshlrev_b32_e32 v6, 16, v96
	v_fmac_f32_e32 v4, v6, v6
	v_lshlrev_b32_e32 v7, 16, v97
	v_and_b32_e32 v6, 0xffff0000, v96
	v_pk_mul_f32 v[6:7], v[6:7], v[6:7]
	s_nop 0
	v_add_f32_e32 v4, v6, v4
	v_add_f32_e32 v4, v7, v4
	v_lshlrev_b32_e32 v7, 16, v98
	v_and_b32_e32 v6, 0xffff0000, v97
	v_pk_mul_f32 v[6:7], v[6:7], v[6:7]
	s_nop 0
	v_add_f32_e32 v4, v6, v4
	v_add_f32_e32 v4, v7, v4
	v_lshlrev_b32_e32 v7, 16, v99
	v_and_b32_e32 v6, 0xffff0000, v98
	v_pk_mul_f32 v[6:7], v[6:7], v[6:7]
	s_nop 0
	v_add_f32_e32 v4, v6, v4
	v_add_f32_e32 v6, v7, v4
	v_and_b32_e32 v4, 0xffff0000, v99
	v_fmac_f32_e32 v6, v4, v4
	v_lshlrev_b32_e32 v4, 16, v124
	v_lshlrev_b32_e32 v25, 16, v125
	v_and_b32_e32 v24, 0xffff0000, v124
	v_fmac_f32_e32 v6, v4, v4
	v_pk_mul_f32 v[24:25], v[24:25], v[24:25]
	v_lshlrev_b32_e32 v7, 16, v126
	v_add_f32_e32 v4, v24, v6
	v_and_b32_e32 v6, 0xffff0000, v125
	v_add_f32_e32 v4, v25, v4
	v_pk_mul_f32 v[6:7], v[6:7], v[6:7]
	s_nop 0
	v_add_f32_e32 v4, v6, v4
	v_add_f32_e32 v4, v7, v4
	v_lshlrev_b32_e32 v7, 16, v127
	v_and_b32_e32 v6, 0xffff0000, v126
	v_pk_mul_f32 v[6:7], v[6:7], v[6:7]
	s_nop 0
	v_add_f32_e32 v4, v6, v4
	v_add_f32_e32 v4, v7, v4
	v_and_b32_e32 v6, 0xffff0000, v127
	v_fmac_f32_e32 v4, v6, v6
	v_lshlrev_b32_e32 v6, 16, v120
	v_fmac_f32_e32 v4, v6, v6
	v_lshlrev_b32_e32 v7, 16, v121
	v_and_b32_e32 v6, 0xffff0000, v120
	v_pk_mul_f32 v[6:7], v[6:7], v[6:7]
	s_nop 0
	v_add_f32_e32 v4, v6, v4
	v_add_f32_e32 v4, v7, v4
	v_lshlrev_b32_e32 v7, 16, v122
	v_and_b32_e32 v6, 0xffff0000, v121
	v_pk_mul_f32 v[6:7], v[6:7], v[6:7]
	s_nop 0
	v_add_f32_e32 v4, v6, v4
	v_add_f32_e32 v4, v7, v4
	v_lshlrev_b32_e32 v7, 16, v123
	v_and_b32_e32 v6, 0xffff0000, v122
	v_pk_mul_f32 v[6:7], v[6:7], v[6:7]
	s_nop 0
	v_add_f32_e32 v4, v6, v4
	v_add_f32_e32 v4, v7, v4
	v_and_b32_e32 v6, 0xffff0000, v123
	v_fmac_f32_e32 v4, v6, v6
	v_lshlrev_b32_e32 v6, 16, v116
	v_fmac_f32_e32 v4, v6, v6
	v_lshlrev_b32_e32 v7, 16, v117
	v_and_b32_e32 v6, 0xffff0000, v116
	v_pk_mul_f32 v[6:7], v[6:7], v[6:7]
	s_nop 0
	v_add_f32_e32 v4, v6, v4
	v_add_f32_e32 v4, v7, v4
	v_lshlrev_b32_e32 v7, 16, v118
	v_and_b32_e32 v6, 0xffff0000, v117
	v_pk_mul_f32 v[6:7], v[6:7], v[6:7]
	s_nop 0
	v_add_f32_e32 v4, v6, v4
	v_add_f32_e32 v4, v7, v4
	v_lshlrev_b32_e32 v7, 16, v119
	v_and_b32_e32 v6, 0xffff0000, v118
	v_pk_mul_f32 v[6:7], v[6:7], v[6:7]
	s_nop 0
	v_add_f32_e32 v4, v6, v4
	v_add_f32_e32 v4, v7, v4
	v_and_b32_e32 v6, 0xffff0000, v119
	v_fmac_f32_e32 v4, v6, v6
	v_lshlrev_b32_e32 v6, 16, v112
	v_fmac_f32_e32 v4, v6, v6
	v_lshlrev_b32_e32 v7, 16, v113
	v_and_b32_e32 v6, 0xffff0000, v112
	v_pk_mul_f32 v[6:7], v[6:7], v[6:7]
	s_nop 0
	v_add_f32_e32 v4, v6, v4
	v_add_f32_e32 v4, v7, v4
	v_lshlrev_b32_e32 v7, 16, v114
	v_and_b32_e32 v6, 0xffff0000, v113
	v_pk_mul_f32 v[6:7], v[6:7], v[6:7]
	s_nop 0
	v_add_f32_e32 v4, v6, v4
	v_add_f32_e32 v4, v7, v4
	v_lshlrev_b32_e32 v7, 16, v115
	v_and_b32_e32 v6, 0xffff0000, v114
	v_pk_mul_f32 v[6:7], v[6:7], v[6:7]
	s_nop 0
	v_add_f32_e32 v4, v6, v4
	v_add_f32_e32 v6, v7, v4
	v_and_b32_e32 v4, 0xffff0000, v115
	v_fmac_f32_e32 v6, v4, v4
	v_lshlrev_b32_e32 v0, 2, v2
	v_bitop3_b32 v4, v0, 4, v190 bitop3:0x6c
	ds_bpermute_b32 v0, v4, v6
	v_readlane_b32 s2, v238, 44
	v_cmp_eq_u32_e64 s[78:79], 0, v5
	s_nop 0
	v_lshl_add_u32 v2, v3, 2, s2
	s_and_saveexec_b64 s[2:3], s[78:79]
	s_cbranch_execz .LBB0_1171
	s_waitcnt lgkmcnt(0)
	v_add_f32_e32 v0, v6, v0
	s_mov_b32 s6, 0x43c00000
	v_div_scale_f32 v1, s[4:5], s6, s6, v0
	v_rcp_f32_e32 v5, v1
	v_div_scale_f32 v6, vcc, v0, s6, v0
	s_mov_b32 s4, 0x800000
	v_fma_f32 v7, -v1, v5, 1.0
	v_fmac_f32_e32 v5, v7, v5
	v_mul_f32_e32 v7, v6, v5
	v_fma_f32 v8, -v1, v7, v6
	v_fmac_f32_e32 v7, v8, v5
	v_fma_f32 v1, -v1, v7, v6
	v_div_fmas_f32 v1, v1, v5, v7
	v_div_fixup_f32 v0, v1, s6, v0
	v_add_f32_e32 v0, 0x358637bd, v0
	v_mul_f32_e32 v1, 0x4b800000, v0
	v_cmp_gt_f32_e32 vcc, s4, v0
	s_nop 1
	v_cndmask_b32_e32 v0, v0, v1, vcc
	v_rsq_f32_e32 v0, v0
	s_nop 0
	v_mul_f32_e32 v1, 0x45800000, v0
	v_cndmask_b32_e32 v0, v0, v1, vcc
	ds_write_b32 v2, v0

; DI float bf2f(unsigned v) { return __uint_as_float(v << 16); }
; DI void rinv_prepass(const u16* __restrict__ A, int K, const pg8::StaticOrder& S, LAS float* tab) {
;     ...
;     const u16* pr = A + (size_t)(u.pm * 256 + row) * K + half * (K >> 1);
;     float ss = 0.f;
;     for (int c = 0; c < (K >> 1); c += 8) {
;       u32x4 w = *(const u32x4*)(pr + c);
;       float a;
;       a = bf2f(w.x & 0xffffu); ss += a * a; a = bf2f(w.x >> 16); ss += a * a;
;       a = bf2f(w.y & 0xffffu); ss += a * a; a = bf2f(w.y >> 16); ss += a * a;
;       a = bf2f(w.z & 0xffffu); ss += a * a; a = bf2f(w.z >> 16); ss += a * a;
;       a = bf2f(w.w & 0xffffu); ss += a * a; a = bf2f(w.w >> 16); ss += a * a;
;     }
.LBB0_1173:
	global_load_dwordx4 v[32:35], v[0:1], off offset:16
	global_load_dwordx4 v[36:39], v[0:1], off
	global_load_dwordx4 v[40:43], v[0:1], off offset:-16
	global_load_dwordx4 v[44:47], v[0:1], off offset:-32
	global_load_dwordx4 v[48:51], v[0:1], off offset:80
	global_load_dwordx4 v[52:55], v[0:1], off offset:64
	global_load_dwordx4 v[56:59], v[0:1], off offset:48
	global_load_dwordx4 v[60:63], v[0:1], off offset:32
	global_load_dwordx4 v[64:67], v[0:1], off offset:144
	global_load_dwordx4 v[68:71], v[0:1], off offset:128
	global_load_dwordx4 v[72:75], v[0:1], off offset:112
	global_load_dwordx4 v[76:79], v[0:1], off offset:96
	global_load_dwordx4 v[80:83], v[0:1], off offset:208
	global_load_dwordx4 v[84:87], v[0:1], off offset:192
	global_load_dwordx4 v[88:91], v[0:1], off offset:176
	global_load_dwordx4 v[92:95], v[0:1], off offset:160
	global_load_dwordx4 v[96:99], v[0:1], off offset:272
	global_load_dwordx4 v[100:103], v[0:1], off offset:256
	global_load_dwordx4 v[104:107], v[0:1], off offset:240
	global_load_dwordx4 v[108:111], v[0:1], off offset:224
	global_load_dwordx4 v[112:115], v[0:1], off offset:336
	global_load_dwordx4 v[116:119], v[0:1], off offset:320
	global_load_dwordx4 v[120:123], v[0:1], off offset:304
	global_load_dwordx4 v[124:127], v[0:1], off offset:288
	s_waitcnt vmcnt(0)
	v_lshlrev_b32_e32 v22, 16, v44
	v_fmac_f32_e32 v5, v22, v22
	v_lshlrev_b32_e32 v23, 16, v45
	v_and_b32_e32 v22, 0xffff0000, v44
	v_pk_mul_f32 v[22:23], v[22:23], v[22:23]
	s_nop 0
	v_add_f32_e32 v5, v22, v5
	v_add_f32_e32 v5, v23, v5
	v_lshlrev_b32_e32 v23, 16, v46
	v_and_b32_e32 v22, 0xffff0000, v45
	v_pk_mul_f32 v[44:45], v[22:23], v[22:23]
	s_nop 0
	v_add_f32_e32 v5, v44, v5
	v_add_f32_e32 v5, v45, v5
	v_lshlrev_b32_e32 v45, 16, v47
	v_and_b32_e32 v44, 0xffff0000, v46
	v_pk_mul_f32 v[44:45], v[44:45], v[44:45]
	s_nop 0
	v_add_f32_e32 v5, v44, v5
	v_add_f32_e32 v5, v45, v5
	v_and_b32_e32 v44, 0xffff0000, v47
	v_fmac_f32_e32 v5, v44, v44
	v_lshlrev_b32_e32 v44, 16, v40
	v_fmac_f32_e32 v5, v44, v44
	v_lshlrev_b32_e32 v45, 16, v41
	v_and_b32_e32 v44, 0xffff0000, v40
	v_pk_mul_f32 v[44:45], v[44:45], v[44:45]
	s_nop 0
	v_add_f32_e32 v5, v44, v5
	v_add_f32_e32 v5, v45, v5
	v_lshlrev_b32_e32 v45, 16, v42
	v_and_b32_e32 v44, 0xffff0000, v41
	v_pk_mul_f32 v[40:41], v[44:45], v[44:45]
	s_nop 0
	v_add_f32_e32 v5, v40, v5
	v_add_f32_e32 v5, v41, v5
	v_lshlrev_b32_e32 v41, 16, v43
	v_and_b32_e32 v40, 0xffff0000, v42
	v_pk_mul_f32 v[40:41], v[40:41], v[40:41]
	s_nop 0
	v_add_f32_e32 v5, v40, v5
	v_add_f32_e32 v5, v41, v5
	v_and_b32_e32 v40, 0xffff0000, v43
	v_fmac_f32_e32 v5, v40, v40
	v_lshlrev_b32_e32 v40, 16, v36
	v_fmac_f32_e32 v5, v40, v40
	v_lshlrev_b32_e32 v41, 16, v37
	v_and_b32_e32 v40, 0xffff0000, v36
	v_pk_mul_f32 v[40:41], v[40:41], v[40:41]
	s_nop 0
	v_add_f32_e32 v5, v40, v5
	v_add_f32_e32 v5, v41, v5
	v_lshlrev_b32_e32 v41, 16, v38
	v_and_b32_e32 v40, 0xffff0000, v37
	v_pk_mul_f32 v[36:37], v[40:41], v[40:41]
	s_nop 0
	v_add_f32_e32 v5, v36, v5
	v_add_f32_e32 v5, v37, v5
	v_lshlrev_b32_e32 v37, 16, v39
	v_and_b32_e32 v36, 0xffff0000, v38
	v_pk_mul_f32 v[36:37], v[36:37], v[36:37]
	s_nop 0
	v_add_f32_e32 v5, v36, v5
	v_add_f32_e32 v5, v37, v5
	v_and_b32_e32 v36, 0xffff0000, v39
	v_fmac_f32_e32 v5, v36, v36
	v_lshlrev_b32_e32 v36, 16, v32
	v_fmac_f32_e32 v5, v36, v36
	v_lshlrev_b32_e32 v37, 16, v33
	v_and_b32_e32 v36, 0xffff0000, v32
	v_pk_mul_f32 v[36:37], v[36:37], v[36:37]
	s_nop 0
	v_add_f32_e32 v5, v36, v5
	v_add_f32_e32 v5, v37, v5
	v_lshlrev_b32_e32 v37, 16, v34
	v_and_b32_e32 v36, 0xffff0000, v33
	v_pk_mul_f32 v[32:33], v[36:37], v[36:37]
	s_nop 0
	v_add_f32_e32 v5, v32, v5
	v_add_f32_e32 v5, v33, v5
	v_lshlrev_b32_e32 v33, 16, v35
	v_and_b32_e32 v32, 0xffff0000, v34
	v_pk_mul_f32 v[32:33], v[32:33], v[32:33]
	s_nop 0
	v_add_f32_e32 v5, v32, v5
	v_add_f32_e32 v5, v33, v5
	v_and_b32_e32 v32, 0xffff0000, v35
	v_fmac_f32_e32 v5, v32, v32
	v_lshlrev_b32_e32 v22, 16, v60
	v_fmac_f32_e32 v5, v22, v22
	v_lshlrev_b32_e32 v23, 16, v61
	v_and_b32_e32 v22, 0xffff0000, v60
	v_pk_mul_f32 v[22:23], v[22:23], v[22:23]
	s_nop 0
	v_add_f32_e32 v5, v22, v5
	v_add_f32_e32 v5, v23, v5
	v_lshlrev_b32_e32 v23, 16, v62
	v_and_b32_e32 v22, 0xffff0000, v61
	v_pk_mul_f32 v[60:61], v[22:23], v[22:23]
	s_nop 0
	v_add_f32_e32 v5, v60, v5
	v_add_f32_e32 v5, v61, v5
	v_lshlrev_b32_e32 v61, 16, v63
	v_and_b32_e32 v60, 0xffff0000, v62
	v_pk_mul_f32 v[60:61], v[60:61], v[60:61]
	s_nop 0
	v_add_f32_e32 v5, v60, v5
	v_add_f32_e32 v5, v61, v5
	v_and_b32_e32 v60, 0xffff0000, v63
	v_fmac_f32_e32 v5, v60, v60
	v_lshlrev_b32_e32 v60, 16, v56
	v_fmac_f32_e32 v5, v60, v60
	v_lshlrev_b32_e32 v61, 16, v57
	v_and_b32_e32 v60, 0xffff0000, v56
	v_pk_mul_f32 v[60:61], v[60:61], v[60:61]
	s_nop 0
	v_add_f32_e32 v5, v60, v5
	v_add_f32_e32 v5, v61, v5
	v_lshlrev_b32_e32 v61, 16, v58
	v_and_b32_e32 v60, 0xffff0000, v57
	v_pk_mul_f32 v[56:57], v[60:61], v[60:61]
	s_nop 0
	v_add_f32_e32 v5, v56, v5
	v_add_f32_e32 v5, v57, v5
	v_lshlrev_b32_e32 v57, 16, v59
	v_and_b32_e32 v56, 0xffff0000, v58
	v_pk_mul_f32 v[56:57], v[56:57], v[56:57]
	s_nop 0
	v_add_f32_e32 v5, v56, v5
	v_add_f32_e32 v5, v57, v5
	v_and_b32_e32 v56, 0xffff0000, v59
	v_fmac_f32_e32 v5, v56, v56
	v_lshlrev_b32_e32 v56, 16, v52
	v_fmac_f32_e32 v5, v56, v56
	v_lshlrev_b32_e32 v57, 16, v53
	v_and_b32_e32 v56, 0xffff0000, v52
	v_pk_mul_f32 v[56:57], v[56:57], v[56:57]
	s_nop 0
	v_add_f32_e32 v5, v56, v5
	v_add_f32_e32 v5, v57, v5
	v_lshlrev_b32_e32 v57, 16, v54
	v_and_b32_e32 v56, 0xffff0000, v53
	v_pk_mul_f32 v[52:53], v[56:57], v[56:57]
	s_nop 0
	v_add_f32_e32 v5, v52, v5
	v_add_f32_e32 v5, v53, v5
	v_lshlrev_b32_e32 v53, 16, v55
; DI float bf2f(unsigned v) { return __uint_as_float(v << 16); }
; DI void rinv_prepass(const u16* __restrict__ A, int K, const pg8::StaticOrder& S, LAS float* tab) {
;     ...
;     for (int c = 0; c < (K >> 1); c += 8) {
;       u32x4 w = *(const u32x4*)(pr + c);
;       float a;
;       a = bf2f(w.x & 0xffffu); ss += a * a; a = bf2f(w.x >> 16); ss += a * a;
;       a = bf2f(w.y & 0xffffu); ss += a * a; a = bf2f(w.y >> 16); ss += a * a;
;       a = bf2f(w.z & 0xffffu); ss += a * a; a = bf2f(w.z >> 16); ss += a * a;
;       a = bf2f(w.w & 0xffffu); ss += a * a; a = bf2f(w.w >> 16); ss += a * a;
;     }
	v_and_b32_e32 v52, 0xffff0000, v54
	v_pk_mul_f32 v[52:53], v[52:53], v[52:53]
	s_nop 0
	v_add_f32_e32 v5, v52, v5
	v_add_f32_e32 v5, v53, v5
	v_and_b32_e32 v52, 0xffff0000, v55
	v_fmac_f32_e32 v5, v52, v52
	v_lshlrev_b32_e32 v52, 16, v48
	v_fmac_f32_e32 v5, v52, v52
	v_lshlrev_b32_e32 v53, 16, v49
	v_and_b32_e32 v52, 0xffff0000, v48
	v_pk_mul_f32 v[52:53], v[52:53], v[52:53]
	s_nop 0
	v_add_f32_e32 v5, v52, v5
	v_add_f32_e32 v5, v53, v5
	v_lshlrev_b32_e32 v53, 16, v50
	v_and_b32_e32 v52, 0xffff0000, v49
	v_pk_mul_f32 v[48:49], v[52:53], v[52:53]
	s_nop 0
	v_add_f32_e32 v5, v48, v5
	v_add_f32_e32 v5, v49, v5
	v_lshlrev_b32_e32 v49, 16, v51
	v_and_b32_e32 v48, 0xffff0000, v50
	v_pk_mul_f32 v[48:49], v[48:49], v[48:49]
	s_nop 0
	v_add_f32_e32 v5, v48, v5
	v_add_f32_e32 v5, v49, v5
	v_and_b32_e32 v48, 0xffff0000, v51
	v_fmac_f32_e32 v5, v48, v48
	v_lshlrev_b32_e32 v22, 16, v76
	v_fmac_f32_e32 v5, v22, v22
	v_lshlrev_b32_e32 v23, 16, v77
	v_and_b32_e32 v22, 0xffff0000, v76
	v_pk_mul_f32 v[22:23], v[22:23], v[22:23]
	s_nop 0
	v_add_f32_e32 v5, v22, v5
	v_add_f32_e32 v5, v23, v5
	v_lshlrev_b32_e32 v23, 16, v78
	v_and_b32_e32 v22, 0xffff0000, v77
	v_pk_mul_f32 v[76:77], v[22:23], v[22:23]
	s_nop 0
	v_add_f32_e32 v5, v76, v5
	v_add_f32_e32 v5, v77, v5
	v_lshlrev_b32_e32 v77, 16, v79
	v_and_b32_e32 v76, 0xffff0000, v78
	v_pk_mul_f32 v[76:77], v[76:77], v[76:77]
	s_nop 0
	v_add_f32_e32 v5, v76, v5
	v_add_f32_e32 v5, v77, v5
	v_and_b32_e32 v76, 0xffff0000, v79
	v_fmac_f32_e32 v5, v76, v76
	v_lshlrev_b32_e32 v76, 16, v72
	v_fmac_f32_e32 v5, v76, v76
	v_lshlrev_b32_e32 v77, 16, v73
	v_and_b32_e32 v76, 0xffff0000, v72
	v_pk_mul_f32 v[76:77], v[76:77], v[76:77]
	s_nop 0
	v_add_f32_e32 v5, v76, v5
	v_add_f32_e32 v5, v77, v5
	v_lshlrev_b32_e32 v77, 16, v74
	v_and_b32_e32 v76, 0xffff0000, v73
	v_pk_mul_f32 v[72:73], v[76:77], v[76:77]
	s_nop 0
	v_add_f32_e32 v5, v72, v5
	v_add_f32_e32 v5, v73, v5
	v_lshlrev_b32_e32 v73, 16, v75
	v_and_b32_e32 v72, 0xffff0000, v74
	v_pk_mul_f32 v[72:73], v[72:73], v[72:73]
	s_nop 0
	v_add_f32_e32 v5, v72, v5
	v_add_f32_e32 v5, v73, v5
	v_and_b32_e32 v72, 0xffff0000, v75
	v_fmac_f32_e32 v5, v72, v72
	v_lshlrev_b32_e32 v72, 16, v68
	v_fmac_f32_e32 v5, v72, v72
	v_lshlrev_b32_e32 v73, 16, v69
	v_and_b32_e32 v72, 0xffff0000, v68
	v_pk_mul_f32 v[72:73], v[72:73], v[72:73]
	s_nop 0
	v_add_f32_e32 v5, v72, v5
	v_add_f32_e32 v5, v73, v5
	v_lshlrev_b32_e32 v73, 16, v70
	v_and_b32_e32 v72, 0xffff0000, v69
	v_pk_mul_f32 v[68:69], v[72:73], v[72:73]
	s_nop 0
	v_add_f32_e32 v5, v68, v5
	v_add_f32_e32 v5, v69, v5
	v_lshlrev_b32_e32 v69, 16, v71
	v_and_b32_e32 v68, 0xffff0000, v70
	v_pk_mul_f32 v[68:69], v[68:69], v[68:69]
	s_nop 0
	v_add_f32_e32 v5, v68, v5
	v_add_f32_e32 v5, v69, v5
	v_and_b32_e32 v68, 0xffff0000, v71
	v_fmac_f32_e32 v5, v68, v68
	v_lshlrev_b32_e32 v68, 16, v64
	v_fmac_f32_e32 v5, v68, v68
	v_lshlrev_b32_e32 v69, 16, v65
	v_and_b32_e32 v68, 0xffff0000, v64
	v_pk_mul_f32 v[68:69], v[68:69], v[68:69]
	s_nop 0
	v_add_f32_e32 v5, v68, v5
	v_add_f32_e32 v5, v69, v5
	v_lshlrev_b32_e32 v69, 16, v66
	v_and_b32_e32 v68, 0xffff0000, v65
	v_pk_mul_f32 v[64:65], v[68:69], v[68:69]
	s_nop 0
	v_add_f32_e32 v5, v64, v5
	v_add_f32_e32 v5, v65, v5
	v_lshlrev_b32_e32 v65, 16, v67
	v_and_b32_e32 v64, 0xffff0000, v66
	v_pk_mul_f32 v[64:65], v[64:65], v[64:65]
	s_nop 0
	v_add_f32_e32 v5, v64, v5
	v_add_f32_e32 v5, v65, v5
	v_and_b32_e32 v64, 0xffff0000, v67
	v_fmac_f32_e32 v5, v64, v64
	v_lshlrev_b32_e32 v22, 16, v92
	v_fmac_f32_e32 v5, v22, v22
	v_lshlrev_b32_e32 v23, 16, v93
	v_and_b32_e32 v22, 0xffff0000, v92
	v_pk_mul_f32 v[22:23], v[22:23], v[22:23]
	s_nop 0
	v_add_f32_e32 v5, v22, v5
	v_add_f32_e32 v5, v23, v5
	v_lshlrev_b32_e32 v23, 16, v94
	v_and_b32_e32 v22, 0xffff0000, v93
	v_pk_mul_f32 v[92:93], v[22:23], v[22:23]
	s_nop 0
	v_add_f32_e32 v5, v92, v5
	v_add_f32_e32 v5, v93, v5
	v_lshlrev_b32_e32 v93, 16, v95
	v_and_b32_e32 v92, 0xffff0000, v94
	v_pk_mul_f32 v[92:93], v[92:93], v[92:93]
	s_nop 0
	v_add_f32_e32 v5, v92, v5
	v_add_f32_e32 v5, v93, v5
	v_and_b32_e32 v92, 0xffff0000, v95
	v_fmac_f32_e32 v5, v92, v92
	v_lshlrev_b32_e32 v92, 16, v88
	v_fmac_f32_e32 v5, v92, v92
	v_lshlrev_b32_e32 v93, 16, v89
	v_and_b32_e32 v92, 0xffff0000, v88
	v_pk_mul_f32 v[92:93], v[92:93], v[92:93]
	s_nop 0
	v_add_f32_e32 v5, v92, v5
	v_add_f32_e32 v5, v93, v5
	v_lshlrev_b32_e32 v93, 16, v90
	v_and_b32_e32 v92, 0xffff0000, v89
	v_pk_mul_f32 v[88:89], v[92:93], v[92:93]
	s_nop 0
	v_add_f32_e32 v5, v88, v5
	v_add_f32_e32 v5, v89, v5
	v_lshlrev_b32_e32 v89, 16, v91
	v_and_b32_e32 v88, 0xffff0000, v90
	v_pk_mul_f32 v[88:89], v[88:89], v[88:89]
	s_nop 0
	v_add_f32_e32 v5, v88, v5
	v_add_f32_e32 v5, v89, v5
	v_and_b32_e32 v88, 0xffff0000, v91
	v_fmac_f32_e32 v5, v88, v88
	v_lshlrev_b32_e32 v88, 16, v84
	v_fmac_f32_e32 v5, v88, v88
	v_lshlrev_b32_e32 v89, 16, v85
	v_and_b32_e32 v88, 0xffff0000, v84
	v_pk_mul_f32 v[88:89], v[88:89], v[88:89]
	s_nop 0
	v_add_f32_e32 v5, v88, v5
	v_add_f32_e32 v5, v89, v5
	v_lshlrev_b32_e32 v89, 16, v86
	v_and_b32_e32 v88, 0xffff0000, v85
	v_pk_mul_f32 v[84:85], v[88:89], v[88:89]
	s_nop 0
	v_add_f32_e32 v5, v84, v5
	v_add_f32_e32 v5, v85, v5
	v_lshlrev_b32_e32 v85, 16, v87
	v_and_b32_e32 v84, 0xffff0000, v86
	v_pk_mul_f32 v[84:85], v[84:85], v[84:85]
	s_nop 0
	v_add_f32_e32 v5, v84, v5
	v_add_f32_e32 v5, v85, v5
	v_and_b32_e32 v84, 0xffff0000, v87
	v_fmac_f32_e32 v5, v84, v84
	v_lshlrev_b32_e32 v84, 16, v80
	v_fmac_f32_e32 v5, v84, v84
	v_lshlrev_b32_e32 v85, 16, v81
	v_and_b32_e32 v84, 0xffff0000, v80
	v_pk_mul_f32 v[84:85], v[84:85], v[84:85]
	s_nop 0
	v_add_f32_e32 v5, v84, v5
	v_add_f32_e32 v5, v85, v5
; DI float bf2f(unsigned v) { return __uint_as_float(v << 16); }
; DI void rinv_prepass(const u16* __restrict__ A, int K, const pg8::StaticOrder& S, LAS float* tab) {
;     ...
;     for (int c = 0; c < (K >> 1); c += 8) {
;       u32x4 w = *(const u32x4*)(pr + c);
;       float a;
;       a = bf2f(w.x & 0xffffu); ss += a * a; a = bf2f(w.x >> 16); ss += a * a;
;       a = bf2f(w.y & 0xffffu); ss += a * a; a = bf2f(w.y >> 16); ss += a * a;
;       a = bf2f(w.z & 0xffffu); ss += a * a; a = bf2f(w.z >> 16); ss += a * a;
;       a = bf2f(w.w & 0xffffu); ss += a * a; a = bf2f(w.w >> 16); ss += a * a;
;     }
;     ss += shx(ss, 1, tid & 63);
;     if (!half) tab[i * 256 + row] = rsqrtf(ss / (float)K + EPS);
	v_lshlrev_b32_e32 v85, 16, v82
	v_and_b32_e32 v84, 0xffff0000, v81
	v_pk_mul_f32 v[80:81], v[84:85], v[84:85]
	s_nop 0
	v_add_f32_e32 v5, v80, v5
	v_add_f32_e32 v5, v81, v5
	v_lshlrev_b32_e32 v81, 16, v83
	v_and_b32_e32 v80, 0xffff0000, v82
	v_pk_mul_f32 v[80:81], v[80:81], v[80:81]
	s_nop 0
	v_add_f32_e32 v5, v80, v5
	v_add_f32_e32 v5, v81, v5
	v_and_b32_e32 v80, 0xffff0000, v83
	v_fmac_f32_e32 v5, v80, v80
	v_lshlrev_b32_e32 v22, 16, v108
	v_fmac_f32_e32 v5, v22, v22
	v_lshlrev_b32_e32 v23, 16, v109
	v_and_b32_e32 v22, 0xffff0000, v108
	v_pk_mul_f32 v[22:23], v[22:23], v[22:23]
	s_nop 0
	v_add_f32_e32 v5, v22, v5
	v_add_f32_e32 v5, v23, v5
	v_lshlrev_b32_e32 v23, 16, v110
	v_and_b32_e32 v22, 0xffff0000, v109
	v_pk_mul_f32 v[108:109], v[22:23], v[22:23]
	s_nop 0
	v_add_f32_e32 v5, v108, v5
	v_add_f32_e32 v5, v109, v5
	v_lshlrev_b32_e32 v109, 16, v111
	v_and_b32_e32 v108, 0xffff0000, v110
	v_pk_mul_f32 v[108:109], v[108:109], v[108:109]
	s_nop 0
	v_add_f32_e32 v5, v108, v5
	v_add_f32_e32 v5, v109, v5
	v_and_b32_e32 v108, 0xffff0000, v111
	v_fmac_f32_e32 v5, v108, v108
	v_lshlrev_b32_e32 v108, 16, v104
	v_fmac_f32_e32 v5, v108, v108
	v_lshlrev_b32_e32 v109, 16, v105
	v_and_b32_e32 v108, 0xffff0000, v104
	v_pk_mul_f32 v[108:109], v[108:109], v[108:109]
	s_nop 0
	v_add_f32_e32 v5, v108, v5
	v_add_f32_e32 v5, v109, v5
	v_lshlrev_b32_e32 v109, 16, v106
	v_and_b32_e32 v108, 0xffff0000, v105
	v_pk_mul_f32 v[104:105], v[108:109], v[108:109]
	s_nop 0
	v_add_f32_e32 v5, v104, v5
	v_add_f32_e32 v5, v105, v5
	v_lshlrev_b32_e32 v105, 16, v107
	v_and_b32_e32 v104, 0xffff0000, v106
	v_pk_mul_f32 v[104:105], v[104:105], v[104:105]
	s_nop 0
	v_add_f32_e32 v5, v104, v5
	v_add_f32_e32 v5, v105, v5
	v_and_b32_e32 v104, 0xffff0000, v107
	v_fmac_f32_e32 v5, v104, v104
	v_lshlrev_b32_e32 v104, 16, v100
	v_fmac_f32_e32 v5, v104, v104
	v_lshlrev_b32_e32 v105, 16, v101
	v_and_b32_e32 v104, 0xffff0000, v100
	v_pk_mul_f32 v[104:105], v[104:105], v[104:105]
	s_nop 0
	v_add_f32_e32 v5, v104, v5
	v_add_f32_e32 v5, v105, v5
	v_lshlrev_b32_e32 v105, 16, v102
	v_and_b32_e32 v104, 0xffff0000, v101
	v_pk_mul_f32 v[100:101], v[104:105], v[104:105]
	s_nop 0
	v_add_f32_e32 v5, v100, v5
	v_add_f32_e32 v5, v101, v5
	v_lshlrev_b32_e32 v101, 16, v103
	v_and_b32_e32 v100, 0xffff0000, v102
	v_pk_mul_f32 v[100:101], v[100:101], v[100:101]
	s_nop 0
	v_add_f32_e32 v5, v100, v5
	v_add_f32_e32 v5, v101, v5
	v_and_b32_e32 v100, 0xffff0000, v103
	v_fmac_f32_e32 v5, v100, v100
	v_lshlrev_b32_e32 v100, 16, v96
	v_fmac_f32_e32 v5, v100, v100
	v_lshlrev_b32_e32 v101, 16, v97
	v_and_b32_e32 v100, 0xffff0000, v96
	v_pk_mul_f32 v[100:101], v[100:101], v[100:101]
	s_nop 0
	v_add_f32_e32 v5, v100, v5
	v_add_f32_e32 v5, v101, v5
	v_lshlrev_b32_e32 v101, 16, v98
	v_and_b32_e32 v100, 0xffff0000, v97
	v_pk_mul_f32 v[96:97], v[100:101], v[100:101]
	s_nop 0
	v_add_f32_e32 v5, v96, v5
	v_add_f32_e32 v5, v97, v5
	v_lshlrev_b32_e32 v97, 16, v99
	v_and_b32_e32 v96, 0xffff0000, v98
	v_pk_mul_f32 v[96:97], v[96:97], v[96:97]
	s_nop 0
	v_add_f32_e32 v5, v96, v5
	v_add_f32_e32 v5, v97, v5
	v_and_b32_e32 v96, 0xffff0000, v99
	v_fmac_f32_e32 v5, v96, v96
	v_lshlrev_b32_e32 v22, 16, v124
	v_fmac_f32_e32 v5, v22, v22
	v_lshlrev_b32_e32 v23, 16, v125
	v_and_b32_e32 v22, 0xffff0000, v124
	v_pk_mul_f32 v[22:23], v[22:23], v[22:23]
	s_nop 0
	v_add_f32_e32 v5, v22, v5
	v_add_f32_e32 v5, v23, v5
	v_lshlrev_b32_e32 v23, 16, v126
	v_and_b32_e32 v22, 0xffff0000, v125
	v_pk_mul_f32 v[124:125], v[22:23], v[22:23]
	s_nop 0
	v_add_f32_e32 v5, v124, v5
	v_add_f32_e32 v5, v125, v5
	v_lshlrev_b32_e32 v125, 16, v127
	v_and_b32_e32 v124, 0xffff0000, v126
	v_pk_mul_f32 v[124:125], v[124:125], v[124:125]
	s_nop 0
	v_add_f32_e32 v5, v124, v5
	v_add_f32_e32 v5, v125, v5
	v_and_b32_e32 v124, 0xffff0000, v127
	v_fmac_f32_e32 v5, v124, v124
	v_lshlrev_b32_e32 v124, 16, v120
	v_fmac_f32_e32 v5, v124, v124
	v_lshlrev_b32_e32 v125, 16, v121
	v_and_b32_e32 v124, 0xffff0000, v120
	v_pk_mul_f32 v[124:125], v[124:125], v[124:125]
	s_nop 0
	v_add_f32_e32 v5, v124, v5
	v_add_f32_e32 v5, v125, v5
	v_lshlrev_b32_e32 v125, 16, v122
	v_and_b32_e32 v124, 0xffff0000, v121
	v_pk_mul_f32 v[120:121], v[124:125], v[124:125]
	s_nop 0
	v_add_f32_e32 v5, v120, v5
	v_add_f32_e32 v5, v121, v5
	v_lshlrev_b32_e32 v121, 16, v123
	v_and_b32_e32 v120, 0xffff0000, v122
	v_pk_mul_f32 v[120:121], v[120:121], v[120:121]
	s_nop 0
	v_add_f32_e32 v5, v120, v5
	v_add_f32_e32 v5, v121, v5
	v_and_b32_e32 v120, 0xffff0000, v123
	v_fmac_f32_e32 v5, v120, v120
	v_lshlrev_b32_e32 v120, 16, v116
	v_fmac_f32_e32 v5, v120, v120
	v_lshlrev_b32_e32 v121, 16, v117
	v_and_b32_e32 v120, 0xffff0000, v116
	v_pk_mul_f32 v[120:121], v[120:121], v[120:121]
	s_nop 0
	v_add_f32_e32 v5, v120, v5
	v_add_f32_e32 v5, v121, v5
	v_lshlrev_b32_e32 v121, 16, v118
	v_and_b32_e32 v120, 0xffff0000, v117
	v_pk_mul_f32 v[116:117], v[120:121], v[120:121]
	s_nop 0
	v_add_f32_e32 v5, v116, v5
	v_add_f32_e32 v5, v117, v5
	v_lshlrev_b32_e32 v117, 16, v119
	v_and_b32_e32 v116, 0xffff0000, v118
	v_pk_mul_f32 v[116:117], v[116:117], v[116:117]
	s_nop 0
	v_add_f32_e32 v5, v116, v5
	v_add_f32_e32 v5, v117, v5
	v_and_b32_e32 v116, 0xffff0000, v119
	v_fmac_f32_e32 v5, v116, v116
	v_lshlrev_b32_e32 v116, 16, v112
	v_fmac_f32_e32 v5, v116, v116
	v_lshlrev_b32_e32 v117, 16, v113
	v_and_b32_e32 v116, 0xffff0000, v112
	v_pk_mul_f32 v[116:117], v[116:117], v[116:117]
	s_nop 0
	v_add_f32_e32 v5, v116, v5
	v_add_f32_e32 v5, v117, v5
	v_lshlrev_b32_e32 v117, 16, v114
	v_and_b32_e32 v116, 0xffff0000, v113
	v_pk_mul_f32 v[112:113], v[116:117], v[116:117]
	s_nop 0
	v_add_f32_e32 v5, v112, v5
	v_add_f32_e32 v5, v113, v5
	v_lshlrev_b32_e32 v113, 16, v115
	v_and_b32_e32 v112, 0xffff0000, v114
	v_pk_mul_f32 v[112:113], v[112:113], v[112:113]
	s_nop 0
	v_add_f32_e32 v5, v112, v5
	v_add_f32_e32 v5, v113, v5
	v_and_b32_e32 v112, 0xffff0000, v115
	v_fmac_f32_e32 v5, v112, v112
	ds_bpermute_b32 v0, v4, v5
	s_and_saveexec_b64 s[2:3], s[78:79]
	s_cbranch_execz .LBB0_1176
	s_waitcnt lgkmcnt(0)
	v_add_f32_e32 v0, v5, v0
	s_mov_b32 s6, 0x43c00000
	v_div_scale_f32 v1, s[4:5], s6, s6, v0
	v_rcp_f32_e32 v5, v1
	v_div_scale_f32 v6, vcc, v0, s6, v0
	s_mov_b32 s4, 0x800000
	v_fma_f32 v7, -v1, v5, 1.0
	v_fmac_f32_e32 v5, v7, v5
	v_mul_f32_e32 v7, v6, v5
	v_fma_f32 v8, -v1, v7, v6
	v_fmac_f32_e32 v7, v8, v5
	v_fma_f32 v1, -v1, v7, v6
	v_div_fmas_f32 v1, v1, v5, v7
	v_div_fixup_f32 v0, v1, s6, v0
	v_add_f32_e32 v0, 0x358637bd, v0
	v_mul_f32_e32 v1, 0x4b800000, v0
	v_cmp_gt_f32_e32 vcc, s4, v0
	s_nop 1
	v_cndmask_b32_e32 v0, v0, v1, vcc
	v_rsq_f32_e32 v0, v0
	s_nop 0
	v_mul_f32_e32 v1, 0x45800000, v0
	v_cndmask_b32_e32 v0, v0, v1, vcc
	ds_write_b32 v2, v0 offset:1024

; DI float bf2f(unsigned v) { return __uint_as_float(v << 16); }
; DI void rinv_prepass(const u16* __restrict__ A, int K, const pg8::StaticOrder& S, LAS float* tab) {
;     ...
;     const u16* pr = A + (size_t)(u.pm * 256 + row) * K + half * (K >> 1);
;     float ss = 0.f;
;     for (int c = 0; c < (K >> 1); c += 8) {
;       u32x4 w = *(const u32x4*)(pr + c);
;       float a;
;       a = bf2f(w.x & 0xffffu); ss += a * a; a = bf2f(w.x >> 16); ss += a * a;
;       a = bf2f(w.y & 0xffffu); ss += a * a; a = bf2f(w.y >> 16); ss += a * a;
;       a = bf2f(w.z & 0xffffu); ss += a * a; a = bf2f(w.z >> 16); ss += a * a;
;       a = bf2f(w.w & 0xffffu); ss += a * a; a = bf2f(w.w >> 16); ss += a * a;
;     }
.LBB0_1178:
	global_load_dwordx4 v[32:35], v[0:1], off offset:16
	global_load_dwordx4 v[36:39], v[0:1], off
	global_load_dwordx4 v[40:43], v[0:1], off offset:-16
	global_load_dwordx4 v[44:47], v[0:1], off offset:-32
	global_load_dwordx4 v[48:51], v[0:1], off offset:80
	global_load_dwordx4 v[52:55], v[0:1], off offset:64
	global_load_dwordx4 v[56:59], v[0:1], off offset:48
	global_load_dwordx4 v[60:63], v[0:1], off offset:32
	global_load_dwordx4 v[64:67], v[0:1], off offset:144
	global_load_dwordx4 v[68:71], v[0:1], off offset:128
	global_load_dwordx4 v[72:75], v[0:1], off offset:112
	global_load_dwordx4 v[76:79], v[0:1], off offset:96
	global_load_dwordx4 v[80:83], v[0:1], off offset:208
	global_load_dwordx4 v[84:87], v[0:1], off offset:192
	global_load_dwordx4 v[88:91], v[0:1], off offset:176
	global_load_dwordx4 v[92:95], v[0:1], off offset:160
	global_load_dwordx4 v[96:99], v[0:1], off offset:272
	global_load_dwordx4 v[100:103], v[0:1], off offset:256
	global_load_dwordx4 v[104:107], v[0:1], off offset:240
	global_load_dwordx4 v[108:111], v[0:1], off offset:224
	global_load_dwordx4 v[112:115], v[0:1], off offset:336
	global_load_dwordx4 v[116:119], v[0:1], off offset:320
	global_load_dwordx4 v[120:123], v[0:1], off offset:304
	global_load_dwordx4 v[124:127], v[0:1], off offset:288
	s_waitcnt vmcnt(0)
	v_lshlrev_b32_e32 v22, 16, v44
	v_fmac_f32_e32 v5, v22, v22
	v_lshlrev_b32_e32 v23, 16, v45
	v_and_b32_e32 v22, 0xffff0000, v44
	v_pk_mul_f32 v[22:23], v[22:23], v[22:23]
	s_nop 0
	v_add_f32_e32 v5, v22, v5
	v_add_f32_e32 v5, v23, v5
	v_lshlrev_b32_e32 v23, 16, v46
	v_and_b32_e32 v22, 0xffff0000, v45
	v_pk_mul_f32 v[44:45], v[22:23], v[22:23]
	s_nop 0
	v_add_f32_e32 v5, v44, v5
	v_add_f32_e32 v5, v45, v5
	v_lshlrev_b32_e32 v45, 16, v47
	v_and_b32_e32 v44, 0xffff0000, v46
	v_pk_mul_f32 v[44:45], v[44:45], v[44:45]
	s_nop 0
	v_add_f32_e32 v5, v44, v5
	v_add_f32_e32 v5, v45, v5
	v_and_b32_e32 v44, 0xffff0000, v47
	v_fmac_f32_e32 v5, v44, v44
	v_lshlrev_b32_e32 v44, 16, v40
	v_fmac_f32_e32 v5, v44, v44
	v_lshlrev_b32_e32 v45, 16, v41
	v_and_b32_e32 v44, 0xffff0000, v40
	v_pk_mul_f32 v[44:45], v[44:45], v[44:45]
	s_nop 0
	v_add_f32_e32 v5, v44, v5
	v_add_f32_e32 v5, v45, v5
	v_lshlrev_b32_e32 v45, 16, v42
	v_and_b32_e32 v44, 0xffff0000, v41
	v_pk_mul_f32 v[40:41], v[44:45], v[44:45]
	s_nop 0
	v_add_f32_e32 v5, v40, v5
	v_add_f32_e32 v5, v41, v5
	v_lshlrev_b32_e32 v41, 16, v43
	v_and_b32_e32 v40, 0xffff0000, v42
	v_pk_mul_f32 v[40:41], v[40:41], v[40:41]
	s_nop 0
	v_add_f32_e32 v5, v40, v5
	v_add_f32_e32 v5, v41, v5
	v_and_b32_e32 v40, 0xffff0000, v43
	v_fmac_f32_e32 v5, v40, v40
	v_lshlrev_b32_e32 v40, 16, v36
	v_fmac_f32_e32 v5, v40, v40
	v_lshlrev_b32_e32 v41, 16, v37
	v_and_b32_e32 v40, 0xffff0000, v36
	v_pk_mul_f32 v[40:41], v[40:41], v[40:41]
	s_nop 0
	v_add_f32_e32 v5, v40, v5
	v_add_f32_e32 v5, v41, v5
	v_lshlrev_b32_e32 v41, 16, v38
	v_and_b32_e32 v40, 0xffff0000, v37
	v_pk_mul_f32 v[36:37], v[40:41], v[40:41]
	s_nop 0
	v_add_f32_e32 v5, v36, v5
	v_add_f32_e32 v5, v37, v5
	v_lshlrev_b32_e32 v37, 16, v39
	v_and_b32_e32 v36, 0xffff0000, v38
	v_pk_mul_f32 v[36:37], v[36:37], v[36:37]
	s_nop 0
	v_add_f32_e32 v5, v36, v5
	v_add_f32_e32 v5, v37, v5
	v_and_b32_e32 v36, 0xffff0000, v39
	v_fmac_f32_e32 v5, v36, v36
	v_lshlrev_b32_e32 v36, 16, v32
	v_fmac_f32_e32 v5, v36, v36
	v_lshlrev_b32_e32 v37, 16, v33
	v_and_b32_e32 v36, 0xffff0000, v32
	v_pk_mul_f32 v[36:37], v[36:37], v[36:37]
	s_nop 0
	v_add_f32_e32 v5, v36, v5
	v_add_f32_e32 v5, v37, v5
	v_lshlrev_b32_e32 v37, 16, v34
	v_and_b32_e32 v36, 0xffff0000, v33
	v_pk_mul_f32 v[32:33], v[36:37], v[36:37]
	s_nop 0
	v_add_f32_e32 v5, v32, v5
	v_add_f32_e32 v5, v33, v5
	v_lshlrev_b32_e32 v33, 16, v35
	v_and_b32_e32 v32, 0xffff0000, v34
	v_pk_mul_f32 v[32:33], v[32:33], v[32:33]
	s_nop 0
	v_add_f32_e32 v5, v32, v5
	v_add_f32_e32 v5, v33, v5
	v_and_b32_e32 v32, 0xffff0000, v35
	v_fmac_f32_e32 v5, v32, v32
	v_lshlrev_b32_e32 v22, 16, v60
	v_fmac_f32_e32 v5, v22, v22
	v_lshlrev_b32_e32 v23, 16, v61
	v_and_b32_e32 v22, 0xffff0000, v60
	v_pk_mul_f32 v[22:23], v[22:23], v[22:23]
	s_nop 0
	v_add_f32_e32 v5, v22, v5
	v_add_f32_e32 v5, v23, v5
	v_lshlrev_b32_e32 v23, 16, v62
	v_and_b32_e32 v22, 0xffff0000, v61
	v_pk_mul_f32 v[60:61], v[22:23], v[22:23]
	s_nop 0
	v_add_f32_e32 v5, v60, v5
	v_add_f32_e32 v5, v61, v5
	v_lshlrev_b32_e32 v61, 16, v63
	v_and_b32_e32 v60, 0xffff0000, v62
	v_pk_mul_f32 v[60:61], v[60:61], v[60:61]
	s_nop 0
	v_add_f32_e32 v5, v60, v5
	v_add_f32_e32 v5, v61, v5
	v_and_b32_e32 v60, 0xffff0000, v63
	v_fmac_f32_e32 v5, v60, v60
	v_lshlrev_b32_e32 v60, 16, v56
	v_fmac_f32_e32 v5, v60, v60
	v_lshlrev_b32_e32 v61, 16, v57
	v_and_b32_e32 v60, 0xffff0000, v56
	v_pk_mul_f32 v[60:61], v[60:61], v[60:61]
	s_nop 0
	v_add_f32_e32 v5, v60, v5
	v_add_f32_e32 v5, v61, v5
	v_lshlrev_b32_e32 v61, 16, v58
	v_and_b32_e32 v60, 0xffff0000, v57
	v_pk_mul_f32 v[56:57], v[60:61], v[60:61]
	s_nop 0
	v_add_f32_e32 v5, v56, v5
	v_add_f32_e32 v5, v57, v5
	v_lshlrev_b32_e32 v57, 16, v59
	v_and_b32_e32 v56, 0xffff0000, v58
	v_pk_mul_f32 v[56:57], v[56:57], v[56:57]
	s_nop 0
	v_add_f32_e32 v5, v56, v5
	v_add_f32_e32 v5, v57, v5
	v_and_b32_e32 v56, 0xffff0000, v59
	v_fmac_f32_e32 v5, v56, v56
	v_lshlrev_b32_e32 v56, 16, v52
	v_fmac_f32_e32 v5, v56, v56
	v_lshlrev_b32_e32 v57, 16, v53
	v_and_b32_e32 v56, 0xffff0000, v52
	v_pk_mul_f32 v[56:57], v[56:57], v[56:57]
	s_nop 0
	v_add_f32_e32 v5, v56, v5
	v_add_f32_e32 v5, v57, v5
	v_lshlrev_b32_e32 v57, 16, v54
	v_and_b32_e32 v56, 0xffff0000, v53
	v_pk_mul_f32 v[52:53], v[56:57], v[56:57]
	s_nop 0
	v_add_f32_e32 v5, v52, v5
	v_add_f32_e32 v5, v53, v5
	v_lshlrev_b32_e32 v53, 16, v55
; DI float bf2f(unsigned v) { return __uint_as_float(v << 16); }
; DI void rinv_prepass(const u16* __restrict__ A, int K, const pg8::StaticOrder& S, LAS float* tab) {
;     ...
;     for (int c = 0; c < (K >> 1); c += 8) {
;       u32x4 w = *(const u32x4*)(pr + c);
;       float a;
;       a = bf2f(w.x & 0xffffu); ss += a * a; a = bf2f(w.x >> 16); ss += a * a;
;       a = bf2f(w.y & 0xffffu); ss += a * a; a = bf2f(w.y >> 16); ss += a * a;
;       a = bf2f(w.z & 0xffffu); ss += a * a; a = bf2f(w.z >> 16); ss += a * a;
;       a = bf2f(w.w & 0xffffu); ss += a * a; a = bf2f(w.w >> 16); ss += a * a;
;     }
	v_and_b32_e32 v52, 0xffff0000, v54
	v_pk_mul_f32 v[52:53], v[52:53], v[52:53]
	s_nop 0
	v_add_f32_e32 v5, v52, v5
	v_add_f32_e32 v5, v53, v5
	v_and_b32_e32 v52, 0xffff0000, v55
	v_fmac_f32_e32 v5, v52, v52
	v_lshlrev_b32_e32 v52, 16, v48
	v_fmac_f32_e32 v5, v52, v52
	v_lshlrev_b32_e32 v53, 16, v49
	v_and_b32_e32 v52, 0xffff0000, v48
	v_pk_mul_f32 v[52:53], v[52:53], v[52:53]
	s_nop 0
	v_add_f32_e32 v5, v52, v5
	v_add_f32_e32 v5, v53, v5
	v_lshlrev_b32_e32 v53, 16, v50
	v_and_b32_e32 v52, 0xffff0000, v49
	v_pk_mul_f32 v[48:49], v[52:53], v[52:53]
	s_nop 0
	v_add_f32_e32 v5, v48, v5
	v_add_f32_e32 v5, v49, v5
	v_lshlrev_b32_e32 v49, 16, v51
	v_and_b32_e32 v48, 0xffff0000, v50
	v_pk_mul_f32 v[48:49], v[48:49], v[48:49]
	s_nop 0
	v_add_f32_e32 v5, v48, v5
	v_add_f32_e32 v5, v49, v5
	v_and_b32_e32 v48, 0xffff0000, v51
	v_fmac_f32_e32 v5, v48, v48
	v_lshlrev_b32_e32 v22, 16, v76
	v_fmac_f32_e32 v5, v22, v22
	v_lshlrev_b32_e32 v23, 16, v77
	v_and_b32_e32 v22, 0xffff0000, v76
	v_pk_mul_f32 v[22:23], v[22:23], v[22:23]
	s_nop 0
	v_add_f32_e32 v5, v22, v5
	v_add_f32_e32 v5, v23, v5
	v_lshlrev_b32_e32 v23, 16, v78
	v_and_b32_e32 v22, 0xffff0000, v77
	v_pk_mul_f32 v[76:77], v[22:23], v[22:23]
	s_nop 0
	v_add_f32_e32 v5, v76, v5
	v_add_f32_e32 v5, v77, v5
	v_lshlrev_b32_e32 v77, 16, v79
	v_and_b32_e32 v76, 0xffff0000, v78
	v_pk_mul_f32 v[76:77], v[76:77], v[76:77]
	s_nop 0
	v_add_f32_e32 v5, v76, v5
	v_add_f32_e32 v5, v77, v5
	v_and_b32_e32 v76, 0xffff0000, v79
	v_fmac_f32_e32 v5, v76, v76
	v_lshlrev_b32_e32 v76, 16, v72
	v_fmac_f32_e32 v5, v76, v76
	v_lshlrev_b32_e32 v77, 16, v73
	v_and_b32_e32 v76, 0xffff0000, v72
	v_pk_mul_f32 v[76:77], v[76:77], v[76:77]
	s_nop 0
	v_add_f32_e32 v5, v76, v5
	v_add_f32_e32 v5, v77, v5
	v_lshlrev_b32_e32 v77, 16, v74
	v_and_b32_e32 v76, 0xffff0000, v73
	v_pk_mul_f32 v[72:73], v[76:77], v[76:77]
	s_nop 0
	v_add_f32_e32 v5, v72, v5
	v_add_f32_e32 v5, v73, v5
	v_lshlrev_b32_e32 v73, 16, v75
	v_and_b32_e32 v72, 0xffff0000, v74
	v_pk_mul_f32 v[72:73], v[72:73], v[72:73]
	s_nop 0
	v_add_f32_e32 v5, v72, v5
	v_add_f32_e32 v5, v73, v5
	v_and_b32_e32 v72, 0xffff0000, v75
	v_fmac_f32_e32 v5, v72, v72
	v_lshlrev_b32_e32 v72, 16, v68
	v_fmac_f32_e32 v5, v72, v72
	v_lshlrev_b32_e32 v73, 16, v69
	v_and_b32_e32 v72, 0xffff0000, v68
	v_pk_mul_f32 v[72:73], v[72:73], v[72:73]
	s_nop 0
	v_add_f32_e32 v5, v72, v5
	v_add_f32_e32 v5, v73, v5
	v_lshlrev_b32_e32 v73, 16, v70
	v_and_b32_e32 v72, 0xffff0000, v69
	v_pk_mul_f32 v[68:69], v[72:73], v[72:73]
	s_nop 0
	v_add_f32_e32 v5, v68, v5
	v_add_f32_e32 v5, v69, v5
	v_lshlrev_b32_e32 v69, 16, v71
	v_and_b32_e32 v68, 0xffff0000, v70
	v_pk_mul_f32 v[68:69], v[68:69], v[68:69]
	s_nop 0
	v_add_f32_e32 v5, v68, v5
	v_add_f32_e32 v5, v69, v5
	v_and_b32_e32 v68, 0xffff0000, v71
	v_fmac_f32_e32 v5, v68, v68
	v_lshlrev_b32_e32 v68, 16, v64
	v_fmac_f32_e32 v5, v68, v68
	v_lshlrev_b32_e32 v69, 16, v65
	v_and_b32_e32 v68, 0xffff0000, v64
	v_pk_mul_f32 v[68:69], v[68:69], v[68:69]
	s_nop 0
	v_add_f32_e32 v5, v68, v5
	v_add_f32_e32 v5, v69, v5
	v_lshlrev_b32_e32 v69, 16, v66
	v_and_b32_e32 v68, 0xffff0000, v65
	v_pk_mul_f32 v[64:65], v[68:69], v[68:69]
	s_nop 0
	v_add_f32_e32 v5, v64, v5
	v_add_f32_e32 v5, v65, v5
	v_lshlrev_b32_e32 v65, 16, v67
	v_and_b32_e32 v64, 0xffff0000, v66
	v_pk_mul_f32 v[64:65], v[64:65], v[64:65]
	s_nop 0
	v_add_f32_e32 v5, v64, v5
	v_add_f32_e32 v5, v65, v5
	v_and_b32_e32 v64, 0xffff0000, v67
	v_fmac_f32_e32 v5, v64, v64
	v_lshlrev_b32_e32 v22, 16, v92
	v_fmac_f32_e32 v5, v22, v22
	v_lshlrev_b32_e32 v23, 16, v93
	v_and_b32_e32 v22, 0xffff0000, v92
	v_pk_mul_f32 v[22:23], v[22:23], v[22:23]
	s_nop 0
	v_add_f32_e32 v5, v22, v5
	v_add_f32_e32 v5, v23, v5
	v_lshlrev_b32_e32 v23, 16, v94
	v_and_b32_e32 v22, 0xffff0000, v93
	v_pk_mul_f32 v[92:93], v[22:23], v[22:23]
	s_nop 0
	v_add_f32_e32 v5, v92, v5
	v_add_f32_e32 v5, v93, v5
	v_lshlrev_b32_e32 v93, 16, v95
	v_and_b32_e32 v92, 0xffff0000, v94
	v_pk_mul_f32 v[92:93], v[92:93], v[92:93]
	s_nop 0
	v_add_f32_e32 v5, v92, v5
	v_add_f32_e32 v5, v93, v5
	v_and_b32_e32 v92, 0xffff0000, v95
	v_fmac_f32_e32 v5, v92, v92
	v_lshlrev_b32_e32 v92, 16, v88
	v_fmac_f32_e32 v5, v92, v92
	v_lshlrev_b32_e32 v93, 16, v89
	v_and_b32_e32 v92, 0xffff0000, v88
	v_pk_mul_f32 v[92:93], v[92:93], v[92:93]
	s_nop 0
	v_add_f32_e32 v5, v92, v5
	v_add_f32_e32 v5, v93, v5
	v_lshlrev_b32_e32 v93, 16, v90
	v_and_b32_e32 v92, 0xffff0000, v89
	v_pk_mul_f32 v[88:89], v[92:93], v[92:93]
	s_nop 0
	v_add_f32_e32 v5, v88, v5
	v_add_f32_e32 v5, v89, v5
	v_lshlrev_b32_e32 v89, 16, v91
	v_and_b32_e32 v88, 0xffff0000, v90
	v_pk_mul_f32 v[88:89], v[88:89], v[88:89]
	s_nop 0
	v_add_f32_e32 v5, v88, v5
	v_add_f32_e32 v5, v89, v5
	v_and_b32_e32 v88, 0xffff0000, v91
	v_fmac_f32_e32 v5, v88, v88
	v_lshlrev_b32_e32 v88, 16, v84
	v_fmac_f32_e32 v5, v88, v88
	v_lshlrev_b32_e32 v89, 16, v85
	v_and_b32_e32 v88, 0xffff0000, v84
	v_pk_mul_f32 v[88:89], v[88:89], v[88:89]
	s_nop 0
	v_add_f32_e32 v5, v88, v5
	v_add_f32_e32 v5, v89, v5
	v_lshlrev_b32_e32 v89, 16, v86
	v_and_b32_e32 v88, 0xffff0000, v85
	v_pk_mul_f32 v[84:85], v[88:89], v[88:89]
	s_nop 0
	v_add_f32_e32 v5, v84, v5
	v_add_f32_e32 v5, v85, v5
	v_lshlrev_b32_e32 v85, 16, v87
	v_and_b32_e32 v84, 0xffff0000, v86
	v_pk_mul_f32 v[84:85], v[84:85], v[84:85]
	s_nop 0
	v_add_f32_e32 v5, v84, v5
	v_add_f32_e32 v5, v85, v5
	v_and_b32_e32 v84, 0xffff0000, v87
	v_fmac_f32_e32 v5, v84, v84
	v_lshlrev_b32_e32 v84, 16, v80
	v_fmac_f32_e32 v5, v84, v84
	v_lshlrev_b32_e32 v85, 16, v81
	v_and_b32_e32 v84, 0xffff0000, v80
	v_pk_mul_f32 v[84:85], v[84:85], v[84:85]
	s_nop 0
	v_add_f32_e32 v5, v84, v5
	v_add_f32_e32 v5, v85, v5
; DI float bf2f(unsigned v) { return __uint_as_float(v << 16); }
; DI void rinv_prepass(const u16* __restrict__ A, int K, const pg8::StaticOrder& S, LAS float* tab) {
;     ...
;     for (int c = 0; c < (K >> 1); c += 8) {
;       u32x4 w = *(const u32x4*)(pr + c);
;       float a;
;       a = bf2f(w.x & 0xffffu); ss += a * a; a = bf2f(w.x >> 16); ss += a * a;
;       a = bf2f(w.y & 0xffffu); ss += a * a; a = bf2f(w.y >> 16); ss += a * a;
;       a = bf2f(w.z & 0xffffu); ss += a * a; a = bf2f(w.z >> 16); ss += a * a;
;       a = bf2f(w.w & 0xffffu); ss += a * a; a = bf2f(w.w >> 16); ss += a * a;
;     }
;     ss += shx(ss, 1, tid & 63);
;     if (!half) tab[i * 256 + row] = rsqrtf(ss / (float)K + EPS);
	v_lshlrev_b32_e32 v85, 16, v82
	v_and_b32_e32 v84, 0xffff0000, v81
	v_pk_mul_f32 v[80:81], v[84:85], v[84:85]
	s_nop 0
	v_add_f32_e32 v5, v80, v5
	v_add_f32_e32 v5, v81, v5
	v_lshlrev_b32_e32 v81, 16, v83
	v_and_b32_e32 v80, 0xffff0000, v82
	v_pk_mul_f32 v[80:81], v[80:81], v[80:81]
	s_nop 0
	v_add_f32_e32 v5, v80, v5
	v_add_f32_e32 v5, v81, v5
	v_and_b32_e32 v80, 0xffff0000, v83
	v_fmac_f32_e32 v5, v80, v80
	v_lshlrev_b32_e32 v22, 16, v108
	v_fmac_f32_e32 v5, v22, v22
	v_lshlrev_b32_e32 v23, 16, v109
	v_and_b32_e32 v22, 0xffff0000, v108
	v_pk_mul_f32 v[22:23], v[22:23], v[22:23]
	s_nop 0
	v_add_f32_e32 v5, v22, v5
	v_add_f32_e32 v5, v23, v5
	v_lshlrev_b32_e32 v23, 16, v110
	v_and_b32_e32 v22, 0xffff0000, v109
	v_pk_mul_f32 v[108:109], v[22:23], v[22:23]
	s_nop 0
	v_add_f32_e32 v5, v108, v5
	v_add_f32_e32 v5, v109, v5
	v_lshlrev_b32_e32 v109, 16, v111
	v_and_b32_e32 v108, 0xffff0000, v110
	v_pk_mul_f32 v[108:109], v[108:109], v[108:109]
	s_nop 0
	v_add_f32_e32 v5, v108, v5
	v_add_f32_e32 v5, v109, v5
	v_and_b32_e32 v108, 0xffff0000, v111
	v_fmac_f32_e32 v5, v108, v108
	v_lshlrev_b32_e32 v108, 16, v104
	v_fmac_f32_e32 v5, v108, v108
	v_lshlrev_b32_e32 v109, 16, v105
	v_and_b32_e32 v108, 0xffff0000, v104
	v_pk_mul_f32 v[108:109], v[108:109], v[108:109]
	s_nop 0
	v_add_f32_e32 v5, v108, v5
	v_add_f32_e32 v5, v109, v5
	v_lshlrev_b32_e32 v109, 16, v106
	v_and_b32_e32 v108, 0xffff0000, v105
	v_pk_mul_f32 v[104:105], v[108:109], v[108:109]
	s_nop 0
	v_add_f32_e32 v5, v104, v5
	v_add_f32_e32 v5, v105, v5
	v_lshlrev_b32_e32 v105, 16, v107
	v_and_b32_e32 v104, 0xffff0000, v106
	v_pk_mul_f32 v[104:105], v[104:105], v[104:105]
	s_nop 0
	v_add_f32_e32 v5, v104, v5
	v_add_f32_e32 v5, v105, v5
	v_and_b32_e32 v104, 0xffff0000, v107
	v_fmac_f32_e32 v5, v104, v104
	v_lshlrev_b32_e32 v104, 16, v100
	v_fmac_f32_e32 v5, v104, v104
	v_lshlrev_b32_e32 v105, 16, v101
	v_and_b32_e32 v104, 0xffff0000, v100
	v_pk_mul_f32 v[104:105], v[104:105], v[104:105]
	s_nop 0
	v_add_f32_e32 v5, v104, v5
	v_add_f32_e32 v5, v105, v5
	v_lshlrev_b32_e32 v105, 16, v102
	v_and_b32_e32 v104, 0xffff0000, v101
	v_pk_mul_f32 v[100:101], v[104:105], v[104:105]
	s_nop 0
	v_add_f32_e32 v5, v100, v5
	v_add_f32_e32 v5, v101, v5
	v_lshlrev_b32_e32 v101, 16, v103
	v_and_b32_e32 v100, 0xffff0000, v102
	v_pk_mul_f32 v[100:101], v[100:101], v[100:101]
	s_nop 0
	v_add_f32_e32 v5, v100, v5
	v_add_f32_e32 v5, v101, v5
	v_and_b32_e32 v100, 0xffff0000, v103
	v_fmac_f32_e32 v5, v100, v100
	v_lshlrev_b32_e32 v100, 16, v96
	v_fmac_f32_e32 v5, v100, v100
	v_lshlrev_b32_e32 v101, 16, v97
	v_and_b32_e32 v100, 0xffff0000, v96
	v_pk_mul_f32 v[100:101], v[100:101], v[100:101]
	s_nop 0
	v_add_f32_e32 v5, v100, v5
	v_add_f32_e32 v5, v101, v5
	v_lshlrev_b32_e32 v101, 16, v98
	v_and_b32_e32 v100, 0xffff0000, v97
	v_pk_mul_f32 v[96:97], v[100:101], v[100:101]
	s_nop 0
	v_add_f32_e32 v5, v96, v5
	v_add_f32_e32 v5, v97, v5
	v_lshlrev_b32_e32 v97, 16, v99
	v_and_b32_e32 v96, 0xffff0000, v98
	v_pk_mul_f32 v[96:97], v[96:97], v[96:97]
	s_nop 0
	v_add_f32_e32 v5, v96, v5
	v_add_f32_e32 v5, v97, v5
	v_and_b32_e32 v96, 0xffff0000, v99
	v_fmac_f32_e32 v5, v96, v96
	v_lshlrev_b32_e32 v22, 16, v124
	v_fmac_f32_e32 v5, v22, v22
	v_lshlrev_b32_e32 v23, 16, v125
	v_and_b32_e32 v22, 0xffff0000, v124
	v_pk_mul_f32 v[22:23], v[22:23], v[22:23]
	s_nop 0
	v_add_f32_e32 v5, v22, v5
	v_add_f32_e32 v5, v23, v5
	v_lshlrev_b32_e32 v23, 16, v126
	v_and_b32_e32 v22, 0xffff0000, v125
	v_pk_mul_f32 v[124:125], v[22:23], v[22:23]
	s_nop 0
	v_add_f32_e32 v5, v124, v5
	v_add_f32_e32 v5, v125, v5
	v_lshlrev_b32_e32 v125, 16, v127
	v_and_b32_e32 v124, 0xffff0000, v126
	v_pk_mul_f32 v[124:125], v[124:125], v[124:125]
	s_nop 0
	v_add_f32_e32 v5, v124, v5
	v_add_f32_e32 v5, v125, v5
	v_and_b32_e32 v124, 0xffff0000, v127
	v_fmac_f32_e32 v5, v124, v124
	v_lshlrev_b32_e32 v124, 16, v120
	v_fmac_f32_e32 v5, v124, v124
	v_lshlrev_b32_e32 v125, 16, v121
	v_and_b32_e32 v124, 0xffff0000, v120
	v_pk_mul_f32 v[124:125], v[124:125], v[124:125]
	s_nop 0
	v_add_f32_e32 v5, v124, v5
	v_add_f32_e32 v5, v125, v5
	v_lshlrev_b32_e32 v125, 16, v122
	v_and_b32_e32 v124, 0xffff0000, v121
	v_pk_mul_f32 v[120:121], v[124:125], v[124:125]
	s_nop 0
	v_add_f32_e32 v5, v120, v5
	v_add_f32_e32 v5, v121, v5
	v_lshlrev_b32_e32 v121, 16, v123
	v_and_b32_e32 v120, 0xffff0000, v122
	v_pk_mul_f32 v[120:121], v[120:121], v[120:121]
	s_nop 0
	v_add_f32_e32 v5, v120, v5
	v_add_f32_e32 v5, v121, v5
	v_and_b32_e32 v120, 0xffff0000, v123
	v_fmac_f32_e32 v5, v120, v120
	v_lshlrev_b32_e32 v120, 16, v116
	v_fmac_f32_e32 v5, v120, v120
	v_lshlrev_b32_e32 v121, 16, v117
	v_and_b32_e32 v120, 0xffff0000, v116
	v_pk_mul_f32 v[120:121], v[120:121], v[120:121]
	s_nop 0
	v_add_f32_e32 v5, v120, v5
	v_add_f32_e32 v5, v121, v5
	v_lshlrev_b32_e32 v121, 16, v118
	v_and_b32_e32 v120, 0xffff0000, v117
	v_pk_mul_f32 v[116:117], v[120:121], v[120:121]
	s_nop 0
	v_add_f32_e32 v5, v116, v5
	v_add_f32_e32 v5, v117, v5
	v_lshlrev_b32_e32 v117, 16, v119
	v_and_b32_e32 v116, 0xffff0000, v118
	v_pk_mul_f32 v[116:117], v[116:117], v[116:117]
	s_nop 0
	v_add_f32_e32 v5, v116, v5
	v_add_f32_e32 v5, v117, v5
	v_and_b32_e32 v116, 0xffff0000, v119
	v_fmac_f32_e32 v5, v116, v116
	v_lshlrev_b32_e32 v116, 16, v112
	v_fmac_f32_e32 v5, v116, v116
	v_lshlrev_b32_e32 v117, 16, v113
	v_and_b32_e32 v116, 0xffff0000, v112
	v_pk_mul_f32 v[116:117], v[116:117], v[116:117]
	s_nop 0
	v_add_f32_e32 v5, v116, v5
	v_add_f32_e32 v5, v117, v5
	v_lshlrev_b32_e32 v117, 16, v114
	v_and_b32_e32 v116, 0xffff0000, v113
	v_pk_mul_f32 v[112:113], v[116:117], v[116:117]
	s_nop 0
	v_add_f32_e32 v5, v112, v5
	v_add_f32_e32 v5, v113, v5
	v_lshlrev_b32_e32 v113, 16, v115
	v_and_b32_e32 v112, 0xffff0000, v114
	v_pk_mul_f32 v[112:113], v[112:113], v[112:113]
	s_nop 0
	v_add_f32_e32 v5, v112, v5
	v_add_f32_e32 v5, v113, v5
	v_and_b32_e32 v112, 0xffff0000, v115
	v_fmac_f32_e32 v5, v112, v112
	ds_bpermute_b32 v0, v4, v5
	s_and_saveexec_b64 s[2:3], s[78:79]
	s_cbranch_execz .LBB0_1181
	s_waitcnt lgkmcnt(0)
	v_add_f32_e32 v0, v5, v0
	s_mov_b32 s6, 0x43c00000
	v_div_scale_f32 v1, s[4:5], s6, s6, v0
	v_rcp_f32_e32 v5, v1
	v_div_scale_f32 v6, vcc, v0, s6, v0
	s_mov_b32 s4, 0x800000
	v_fma_f32 v7, -v1, v5, 1.0
	v_fmac_f32_e32 v5, v7, v5
	v_mul_f32_e32 v7, v6, v5
	v_fma_f32 v8, -v1, v7, v6
	v_fmac_f32_e32 v7, v8, v5
	v_fma_f32 v1, -v1, v7, v6
	v_div_fmas_f32 v1, v1, v5, v7
	v_div_fixup_f32 v0, v1, s6, v0
	v_add_f32_e32 v0, 0x358637bd, v0
	v_mul_f32_e32 v1, 0x4b800000, v0
	v_cmp_gt_f32_e32 vcc, s4, v0
	s_nop 1
	v_cndmask_b32_e32 v0, v0, v1, vcc
	v_rsq_f32_e32 v0, v0
	s_nop 0
	v_mul_f32_e32 v1, 0x45800000, v0
	v_cndmask_b32_e32 v0, v0, v1, vcc
	ds_write_b32 v2, v0 offset:2048

; DI float bf2f(unsigned v) { return __uint_as_float(v << 16); }
; DI void rinv_prepass(const u16* __restrict__ A, int K, const pg8::StaticOrder& S, LAS float* tab) {
;     ...
;     const u16* pr = A + (size_t)(u.pm * 256 + row) * K + half * (K >> 1);
;     float ss = 0.f;
;     for (int c = 0; c < (K >> 1); c += 8) {
;       u32x4 w = *(const u32x4*)(pr + c);
;       float a;
;       a = bf2f(w.x & 0xffffu); ss += a * a; a = bf2f(w.x >> 16); ss += a * a;
;       a = bf2f(w.y & 0xffffu); ss += a * a; a = bf2f(w.y >> 16); ss += a * a;
;       a = bf2f(w.z & 0xffffu); ss += a * a; a = bf2f(w.z >> 16); ss += a * a;
;       a = bf2f(w.w & 0xffffu); ss += a * a; a = bf2f(w.w >> 16); ss += a * a;
;     }
.LBB0_1183:
	global_load_dwordx4 v[32:35], v[0:1], off offset:16
	global_load_dwordx4 v[36:39], v[0:1], off
	global_load_dwordx4 v[40:43], v[0:1], off offset:-16
	global_load_dwordx4 v[44:47], v[0:1], off offset:-32
	global_load_dwordx4 v[48:51], v[0:1], off offset:80
	global_load_dwordx4 v[52:55], v[0:1], off offset:64
	global_load_dwordx4 v[56:59], v[0:1], off offset:48
	global_load_dwordx4 v[60:63], v[0:1], off offset:32
	global_load_dwordx4 v[64:67], v[0:1], off offset:144
	global_load_dwordx4 v[68:71], v[0:1], off offset:128
	global_load_dwordx4 v[72:75], v[0:1], off offset:112
	global_load_dwordx4 v[76:79], v[0:1], off offset:96
	global_load_dwordx4 v[80:83], v[0:1], off offset:208
	global_load_dwordx4 v[84:87], v[0:1], off offset:192
	global_load_dwordx4 v[88:91], v[0:1], off offset:176
	global_load_dwordx4 v[92:95], v[0:1], off offset:160
	global_load_dwordx4 v[96:99], v[0:1], off offset:272
	global_load_dwordx4 v[100:103], v[0:1], off offset:256
	global_load_dwordx4 v[104:107], v[0:1], off offset:240
	global_load_dwordx4 v[108:111], v[0:1], off offset:224
	global_load_dwordx4 v[112:115], v[0:1], off offset:336
	global_load_dwordx4 v[116:119], v[0:1], off offset:320
	global_load_dwordx4 v[120:123], v[0:1], off offset:304
	global_load_dwordx4 v[124:127], v[0:1], off offset:288
	s_waitcnt vmcnt(0)
	v_lshlrev_b32_e32 v5, 16, v44
	v_lshlrev_b32_e32 v23, 16, v45
	v_and_b32_e32 v22, 0xffff0000, v44
	v_fmac_f32_e32 v3, v5, v5
	v_pk_mul_f32 v[22:23], v[22:23], v[22:23]
	v_and_b32_e32 v5, 0xffff0000, v47
	v_add_f32_e32 v3, v22, v3
	v_add_f32_e32 v3, v23, v3
	v_lshlrev_b32_e32 v23, 16, v46
	v_and_b32_e32 v22, 0xffff0000, v45
	v_pk_mul_f32 v[44:45], v[22:23], v[22:23]
	s_nop 0
	v_add_f32_e32 v3, v44, v3
	v_add_f32_e32 v3, v45, v3
	v_lshlrev_b32_e32 v45, 16, v47
	v_and_b32_e32 v44, 0xffff0000, v46
	v_pk_mul_f32 v[44:45], v[44:45], v[44:45]
	s_nop 0
	v_add_f32_e32 v3, v44, v3
	v_add_f32_e32 v3, v45, v3
	v_fmac_f32_e32 v3, v5, v5
	v_lshlrev_b32_e32 v5, 16, v40
	v_lshlrev_b32_e32 v45, 16, v41
	v_and_b32_e32 v44, 0xffff0000, v40
	v_fmac_f32_e32 v3, v5, v5
	v_pk_mul_f32 v[44:45], v[44:45], v[44:45]
	v_and_b32_e32 v5, 0xffff0000, v43
	v_add_f32_e32 v3, v44, v3
	v_add_f32_e32 v3, v45, v3
	v_lshlrev_b32_e32 v45, 16, v42
	v_and_b32_e32 v44, 0xffff0000, v41
	v_pk_mul_f32 v[40:41], v[44:45], v[44:45]
	s_nop 0
	v_add_f32_e32 v3, v40, v3
	v_add_f32_e32 v3, v41, v3
	v_lshlrev_b32_e32 v41, 16, v43
	v_and_b32_e32 v40, 0xffff0000, v42
	v_pk_mul_f32 v[40:41], v[40:41], v[40:41]
	s_nop 0
	v_add_f32_e32 v3, v40, v3
	v_add_f32_e32 v3, v41, v3
	v_fmac_f32_e32 v3, v5, v5
	v_lshlrev_b32_e32 v5, 16, v36
	v_lshlrev_b32_e32 v41, 16, v37
	v_and_b32_e32 v40, 0xffff0000, v36
	v_fmac_f32_e32 v3, v5, v5
	v_pk_mul_f32 v[40:41], v[40:41], v[40:41]
	v_and_b32_e32 v5, 0xffff0000, v39
	v_add_f32_e32 v3, v40, v3
	v_add_f32_e32 v3, v41, v3
	v_lshlrev_b32_e32 v41, 16, v38
	v_and_b32_e32 v40, 0xffff0000, v37
	v_pk_mul_f32 v[36:37], v[40:41], v[40:41]
	s_nop 0
	v_add_f32_e32 v3, v36, v3
	v_add_f32_e32 v3, v37, v3
	v_lshlrev_b32_e32 v37, 16, v39
	v_and_b32_e32 v36, 0xffff0000, v38
	v_pk_mul_f32 v[36:37], v[36:37], v[36:37]
	s_nop 0
	v_add_f32_e32 v3, v36, v3
	v_add_f32_e32 v3, v37, v3
	v_fmac_f32_e32 v3, v5, v5
	v_lshlrev_b32_e32 v5, 16, v32
	v_lshlrev_b32_e32 v37, 16, v33
	v_and_b32_e32 v36, 0xffff0000, v32
	v_fmac_f32_e32 v3, v5, v5
	v_pk_mul_f32 v[36:37], v[36:37], v[36:37]
	v_and_b32_e32 v5, 0xffff0000, v35
	v_add_f32_e32 v3, v36, v3
	v_add_f32_e32 v3, v37, v3
	v_lshlrev_b32_e32 v37, 16, v34
	v_and_b32_e32 v36, 0xffff0000, v33
	v_pk_mul_f32 v[32:33], v[36:37], v[36:37]
	s_nop 0
	v_add_f32_e32 v3, v32, v3
	v_add_f32_e32 v3, v33, v3
	v_lshlrev_b32_e32 v33, 16, v35
	v_and_b32_e32 v32, 0xffff0000, v34
	v_pk_mul_f32 v[32:33], v[32:33], v[32:33]
	s_nop 0
	v_add_f32_e32 v3, v32, v3
	v_add_f32_e32 v3, v33, v3
	v_fmac_f32_e32 v3, v5, v5
	v_lshlrev_b32_e32 v5, 16, v60
	v_lshlrev_b32_e32 v23, 16, v61
	v_and_b32_e32 v22, 0xffff0000, v60
	v_fmac_f32_e32 v3, v5, v5
	v_pk_mul_f32 v[22:23], v[22:23], v[22:23]
	v_and_b32_e32 v5, 0xffff0000, v63
	v_add_f32_e32 v3, v22, v3
	v_add_f32_e32 v3, v23, v3
	v_lshlrev_b32_e32 v23, 16, v62
	v_and_b32_e32 v22, 0xffff0000, v61
	v_pk_mul_f32 v[60:61], v[22:23], v[22:23]
	s_nop 0
	v_add_f32_e32 v3, v60, v3
	v_add_f32_e32 v3, v61, v3
	v_lshlrev_b32_e32 v61, 16, v63
	v_and_b32_e32 v60, 0xffff0000, v62
	v_pk_mul_f32 v[60:61], v[60:61], v[60:61]
	s_nop 0
	v_add_f32_e32 v3, v60, v3
	v_add_f32_e32 v3, v61, v3
	v_fmac_f32_e32 v3, v5, v5
	v_lshlrev_b32_e32 v5, 16, v56
	v_lshlrev_b32_e32 v61, 16, v57
	v_and_b32_e32 v60, 0xffff0000, v56
	v_fmac_f32_e32 v3, v5, v5
	v_pk_mul_f32 v[60:61], v[60:61], v[60:61]
	v_and_b32_e32 v5, 0xffff0000, v59
	v_add_f32_e32 v3, v60, v3
	v_add_f32_e32 v3, v61, v3
	v_lshlrev_b32_e32 v61, 16, v58
	v_and_b32_e32 v60, 0xffff0000, v57
	v_pk_mul_f32 v[56:57], v[60:61], v[60:61]
	s_nop 0
	v_add_f32_e32 v3, v56, v3
	v_add_f32_e32 v3, v57, v3
	v_lshlrev_b32_e32 v57, 16, v59
	v_and_b32_e32 v56, 0xffff0000, v58
	v_pk_mul_f32 v[56:57], v[56:57], v[56:57]
	s_nop 0
	v_add_f32_e32 v3, v56, v3
	v_add_f32_e32 v3, v57, v3
	v_fmac_f32_e32 v3, v5, v5
	v_lshlrev_b32_e32 v5, 16, v52
	v_lshlrev_b32_e32 v57, 16, v53
	v_and_b32_e32 v56, 0xffff0000, v52
	v_fmac_f32_e32 v3, v5, v5
	v_pk_mul_f32 v[56:57], v[56:57], v[56:57]
	v_and_b32_e32 v5, 0xffff0000, v55
	v_add_f32_e32 v3, v56, v3
	v_add_f32_e32 v3, v57, v3
	v_lshlrev_b32_e32 v57, 16, v54
	v_and_b32_e32 v56, 0xffff0000, v53
	v_pk_mul_f32 v[52:53], v[56:57], v[56:57]
	s_nop 0
	v_add_f32_e32 v3, v52, v3
	v_add_f32_e32 v3, v53, v3
	v_lshlrev_b32_e32 v53, 16, v55
	v_and_b32_e32 v52, 0xffff0000, v54
; DI float bf2f(unsigned v) { return __uint_as_float(v << 16); }
; DI void rinv_prepass(const u16* __restrict__ A, int K, const pg8::StaticOrder& S, LAS float* tab) {
;     ...
;     for (int c = 0; c < (K >> 1); c += 8) {
;       u32x4 w = *(const u32x4*)(pr + c);
;       float a;
;       a = bf2f(w.x & 0xffffu); ss += a * a; a = bf2f(w.x >> 16); ss += a * a;
;       a = bf2f(w.y & 0xffffu); ss += a * a; a = bf2f(w.y >> 16); ss += a * a;
;       a = bf2f(w.z & 0xffffu); ss += a * a; a = bf2f(w.z >> 16); ss += a * a;
;       a = bf2f(w.w & 0xffffu); ss += a * a; a = bf2f(w.w >> 16); ss += a * a;
;     }
	v_pk_mul_f32 v[52:53], v[52:53], v[52:53]
	s_nop 0
	v_add_f32_e32 v3, v52, v3
	v_add_f32_e32 v3, v53, v3
	v_fmac_f32_e32 v3, v5, v5
	v_lshlrev_b32_e32 v5, 16, v48
	v_lshlrev_b32_e32 v53, 16, v49
	v_and_b32_e32 v52, 0xffff0000, v48
	v_fmac_f32_e32 v3, v5, v5
	v_pk_mul_f32 v[52:53], v[52:53], v[52:53]
	v_and_b32_e32 v5, 0xffff0000, v51
	v_add_f32_e32 v3, v52, v3
	v_add_f32_e32 v3, v53, v3
	v_lshlrev_b32_e32 v53, 16, v50
	v_and_b32_e32 v52, 0xffff0000, v49
	v_pk_mul_f32 v[48:49], v[52:53], v[52:53]
	s_nop 0
	v_add_f32_e32 v3, v48, v3
	v_add_f32_e32 v3, v49, v3
	v_lshlrev_b32_e32 v49, 16, v51
	v_and_b32_e32 v48, 0xffff0000, v50
	v_pk_mul_f32 v[48:49], v[48:49], v[48:49]
	s_nop 0
	v_add_f32_e32 v3, v48, v3
	v_add_f32_e32 v3, v49, v3
	v_fmac_f32_e32 v3, v5, v5
	v_lshlrev_b32_e32 v5, 16, v76
	v_lshlrev_b32_e32 v23, 16, v77
	v_and_b32_e32 v22, 0xffff0000, v76
	v_fmac_f32_e32 v3, v5, v5
	v_pk_mul_f32 v[22:23], v[22:23], v[22:23]
	v_and_b32_e32 v5, 0xffff0000, v79
	v_add_f32_e32 v3, v22, v3
	v_add_f32_e32 v3, v23, v3
	v_lshlrev_b32_e32 v23, 16, v78
	v_and_b32_e32 v22, 0xffff0000, v77
	v_pk_mul_f32 v[76:77], v[22:23], v[22:23]
	s_nop 0
	v_add_f32_e32 v3, v76, v3
	v_add_f32_e32 v3, v77, v3
	v_lshlrev_b32_e32 v77, 16, v79
	v_and_b32_e32 v76, 0xffff0000, v78
	v_pk_mul_f32 v[76:77], v[76:77], v[76:77]
	s_nop 0
	v_add_f32_e32 v3, v76, v3
	v_add_f32_e32 v3, v77, v3
	v_fmac_f32_e32 v3, v5, v5
	v_lshlrev_b32_e32 v5, 16, v72
	v_lshlrev_b32_e32 v77, 16, v73
	v_and_b32_e32 v76, 0xffff0000, v72
	v_fmac_f32_e32 v3, v5, v5
	v_pk_mul_f32 v[76:77], v[76:77], v[76:77]
	v_and_b32_e32 v5, 0xffff0000, v75
	v_add_f32_e32 v3, v76, v3
	v_add_f32_e32 v3, v77, v3
	v_lshlrev_b32_e32 v77, 16, v74
	v_and_b32_e32 v76, 0xffff0000, v73
	v_pk_mul_f32 v[72:73], v[76:77], v[76:77]
	s_nop 0
	v_add_f32_e32 v3, v72, v3
	v_add_f32_e32 v3, v73, v3
	v_lshlrev_b32_e32 v73, 16, v75
	v_and_b32_e32 v72, 0xffff0000, v74
	v_pk_mul_f32 v[72:73], v[72:73], v[72:73]
	s_nop 0
	v_add_f32_e32 v3, v72, v3
	v_add_f32_e32 v3, v73, v3
	v_fmac_f32_e32 v3, v5, v5
	v_lshlrev_b32_e32 v5, 16, v68
	v_lshlrev_b32_e32 v73, 16, v69
	v_and_b32_e32 v72, 0xffff0000, v68
	v_fmac_f32_e32 v3, v5, v5
	v_pk_mul_f32 v[72:73], v[72:73], v[72:73]
	v_and_b32_e32 v5, 0xffff0000, v71
	v_add_f32_e32 v3, v72, v3
	v_add_f32_e32 v3, v73, v3
	v_lshlrev_b32_e32 v73, 16, v70
	v_and_b32_e32 v72, 0xffff0000, v69
	v_pk_mul_f32 v[68:69], v[72:73], v[72:73]
	s_nop 0
	v_add_f32_e32 v3, v68, v3
	v_add_f32_e32 v3, v69, v3
	v_lshlrev_b32_e32 v69, 16, v71
	v_and_b32_e32 v68, 0xffff0000, v70
	v_pk_mul_f32 v[68:69], v[68:69], v[68:69]
	s_nop 0
	v_add_f32_e32 v3, v68, v3
	v_add_f32_e32 v3, v69, v3
	v_fmac_f32_e32 v3, v5, v5
	v_lshlrev_b32_e32 v5, 16, v64
	v_lshlrev_b32_e32 v69, 16, v65
	v_and_b32_e32 v68, 0xffff0000, v64
	v_fmac_f32_e32 v3, v5, v5
	v_pk_mul_f32 v[68:69], v[68:69], v[68:69]
	v_and_b32_e32 v5, 0xffff0000, v67
	v_add_f32_e32 v3, v68, v3
	v_add_f32_e32 v3, v69, v3
	v_lshlrev_b32_e32 v69, 16, v66
	v_and_b32_e32 v68, 0xffff0000, v65
	v_pk_mul_f32 v[64:65], v[68:69], v[68:69]
	s_nop 0
	v_add_f32_e32 v3, v64, v3
	v_add_f32_e32 v3, v65, v3
	v_lshlrev_b32_e32 v65, 16, v67
	v_and_b32_e32 v64, 0xffff0000, v66
	v_pk_mul_f32 v[64:65], v[64:65], v[64:65]
	s_nop 0
	v_add_f32_e32 v3, v64, v3
	v_add_f32_e32 v3, v65, v3
	v_fmac_f32_e32 v3, v5, v5
	v_lshlrev_b32_e32 v5, 16, v92
	v_lshlrev_b32_e32 v23, 16, v93
	v_and_b32_e32 v22, 0xffff0000, v92
	v_fmac_f32_e32 v3, v5, v5
	v_pk_mul_f32 v[22:23], v[22:23], v[22:23]
	v_and_b32_e32 v5, 0xffff0000, v95
	v_add_f32_e32 v3, v22, v3
	v_add_f32_e32 v3, v23, v3
	v_lshlrev_b32_e32 v23, 16, v94
	v_and_b32_e32 v22, 0xffff0000, v93
	v_pk_mul_f32 v[92:93], v[22:23], v[22:23]
	s_nop 0
	v_add_f32_e32 v3, v92, v3
	v_add_f32_e32 v3, v93, v3
	v_lshlrev_b32_e32 v93, 16, v95
	v_and_b32_e32 v92, 0xffff0000, v94
	v_pk_mul_f32 v[92:93], v[92:93], v[92:93]
	s_nop 0
	v_add_f32_e32 v3, v92, v3
	v_add_f32_e32 v3, v93, v3
	v_fmac_f32_e32 v3, v5, v5
	v_lshlrev_b32_e32 v5, 16, v88
	v_lshlrev_b32_e32 v93, 16, v89
	v_and_b32_e32 v92, 0xffff0000, v88
	v_fmac_f32_e32 v3, v5, v5
	v_pk_mul_f32 v[92:93], v[92:93], v[92:93]
	v_and_b32_e32 v5, 0xffff0000, v91
	v_add_f32_e32 v3, v92, v3
	v_add_f32_e32 v3, v93, v3
	v_lshlrev_b32_e32 v93, 16, v90
	v_and_b32_e32 v92, 0xffff0000, v89
	v_pk_mul_f32 v[88:89], v[92:93], v[92:93]
	s_nop 0
	v_add_f32_e32 v3, v88, v3
	v_add_f32_e32 v3, v89, v3
	v_lshlrev_b32_e32 v89, 16, v91
	v_and_b32_e32 v88, 0xffff0000, v90
	v_pk_mul_f32 v[88:89], v[88:89], v[88:89]
	s_nop 0
	v_add_f32_e32 v3, v88, v3
	v_add_f32_e32 v3, v89, v3
	v_fmac_f32_e32 v3, v5, v5
	v_lshlrev_b32_e32 v5, 16, v84
	v_lshlrev_b32_e32 v89, 16, v85
	v_and_b32_e32 v88, 0xffff0000, v84
	v_fmac_f32_e32 v3, v5, v5
	v_pk_mul_f32 v[88:89], v[88:89], v[88:89]
	v_and_b32_e32 v5, 0xffff0000, v87
	v_add_f32_e32 v3, v88, v3
	v_add_f32_e32 v3, v89, v3
	v_lshlrev_b32_e32 v89, 16, v86
	v_and_b32_e32 v88, 0xffff0000, v85
	v_pk_mul_f32 v[84:85], v[88:89], v[88:89]
	s_nop 0
	v_add_f32_e32 v3, v84, v3
	v_add_f32_e32 v3, v85, v3
	v_lshlrev_b32_e32 v85, 16, v87
	v_and_b32_e32 v84, 0xffff0000, v86
	v_pk_mul_f32 v[84:85], v[84:85], v[84:85]
	s_nop 0
	v_add_f32_e32 v3, v84, v3
	v_add_f32_e32 v3, v85, v3
	v_fmac_f32_e32 v3, v5, v5
	v_lshlrev_b32_e32 v5, 16, v80
	v_lshlrev_b32_e32 v85, 16, v81
	v_and_b32_e32 v84, 0xffff0000, v80
	v_fmac_f32_e32 v3, v5, v5
	v_pk_mul_f32 v[84:85], v[84:85], v[84:85]
	v_and_b32_e32 v5, 0xffff0000, v83
	v_add_f32_e32 v3, v84, v3
	v_add_f32_e32 v3, v85, v3
	v_lshlrev_b32_e32 v85, 16, v82
	v_and_b32_e32 v84, 0xffff0000, v81
	v_pk_mul_f32 v[80:81], v[84:85], v[84:85]
	s_nop 0
	v_add_f32_e32 v3, v80, v3
	v_add_f32_e32 v3, v81, v3
; DI float bf2f(unsigned v) { return __uint_as_float(v << 16); }
; DI void rinv_prepass(const u16* __restrict__ A, int K, const pg8::StaticOrder& S, LAS float* tab) {
;     ...
;     for (int c = 0; c < (K >> 1); c += 8) {
;       u32x4 w = *(const u32x4*)(pr + c);
;       float a;
;       a = bf2f(w.x & 0xffffu); ss += a * a; a = bf2f(w.x >> 16); ss += a * a;
;       a = bf2f(w.y & 0xffffu); ss += a * a; a = bf2f(w.y >> 16); ss += a * a;
;       a = bf2f(w.z & 0xffffu); ss += a * a; a = bf2f(w.z >> 16); ss += a * a;
;       a = bf2f(w.w & 0xffffu); ss += a * a; a = bf2f(w.w >> 16); ss += a * a;
;     }
;     ss += shx(ss, 1, tid & 63);
;     if (!half) tab[i * 256 + row] = rsqrtf(ss / (float)K + EPS);
	v_lshlrev_b32_e32 v81, 16, v83
	v_and_b32_e32 v80, 0xffff0000, v82
	v_pk_mul_f32 v[80:81], v[80:81], v[80:81]
	s_nop 0
	v_add_f32_e32 v3, v80, v3
	v_add_f32_e32 v3, v81, v3
	v_fmac_f32_e32 v3, v5, v5
	v_lshlrev_b32_e32 v5, 16, v108
	v_lshlrev_b32_e32 v23, 16, v109
	v_and_b32_e32 v22, 0xffff0000, v108
	v_fmac_f32_e32 v3, v5, v5
	v_pk_mul_f32 v[22:23], v[22:23], v[22:23]
	v_and_b32_e32 v5, 0xffff0000, v111
	v_add_f32_e32 v3, v22, v3
	v_add_f32_e32 v3, v23, v3
	v_lshlrev_b32_e32 v23, 16, v110
	v_and_b32_e32 v22, 0xffff0000, v109
	v_pk_mul_f32 v[108:109], v[22:23], v[22:23]
	s_nop 0
	v_add_f32_e32 v3, v108, v3
	v_add_f32_e32 v3, v109, v3
	v_lshlrev_b32_e32 v109, 16, v111
	v_and_b32_e32 v108, 0xffff0000, v110
	v_pk_mul_f32 v[108:109], v[108:109], v[108:109]
	s_nop 0
	v_add_f32_e32 v3, v108, v3
	v_add_f32_e32 v3, v109, v3
	v_fmac_f32_e32 v3, v5, v5
	v_lshlrev_b32_e32 v5, 16, v104
	v_lshlrev_b32_e32 v109, 16, v105
	v_and_b32_e32 v108, 0xffff0000, v104
	v_fmac_f32_e32 v3, v5, v5
	v_pk_mul_f32 v[108:109], v[108:109], v[108:109]
	v_and_b32_e32 v5, 0xffff0000, v107
	v_add_f32_e32 v3, v108, v3
	v_add_f32_e32 v3, v109, v3
	v_lshlrev_b32_e32 v109, 16, v106
	v_and_b32_e32 v108, 0xffff0000, v105
	v_pk_mul_f32 v[104:105], v[108:109], v[108:109]
	s_nop 0
	v_add_f32_e32 v3, v104, v3
	v_add_f32_e32 v3, v105, v3
	v_lshlrev_b32_e32 v105, 16, v107
	v_and_b32_e32 v104, 0xffff0000, v106
	v_pk_mul_f32 v[104:105], v[104:105], v[104:105]
	s_nop 0
	v_add_f32_e32 v3, v104, v3
	v_add_f32_e32 v3, v105, v3
	v_fmac_f32_e32 v3, v5, v5
	v_lshlrev_b32_e32 v5, 16, v100
	v_lshlrev_b32_e32 v105, 16, v101
	v_and_b32_e32 v104, 0xffff0000, v100
	v_fmac_f32_e32 v3, v5, v5
	v_pk_mul_f32 v[104:105], v[104:105], v[104:105]
	v_and_b32_e32 v5, 0xffff0000, v103
	v_add_f32_e32 v3, v104, v3
	v_add_f32_e32 v3, v105, v3
	v_lshlrev_b32_e32 v105, 16, v102
	v_and_b32_e32 v104, 0xffff0000, v101
	v_pk_mul_f32 v[100:101], v[104:105], v[104:105]
	s_nop 0
	v_add_f32_e32 v3, v100, v3
	v_add_f32_e32 v3, v101, v3
	v_lshlrev_b32_e32 v101, 16, v103
	v_and_b32_e32 v100, 0xffff0000, v102
	v_pk_mul_f32 v[100:101], v[100:101], v[100:101]
	s_nop 0
	v_add_f32_e32 v3, v100, v3
	v_add_f32_e32 v3, v101, v3
	v_fmac_f32_e32 v3, v5, v5
	v_lshlrev_b32_e32 v5, 16, v96
	v_lshlrev_b32_e32 v101, 16, v97
	v_and_b32_e32 v100, 0xffff0000, v96
	v_fmac_f32_e32 v3, v5, v5
	v_pk_mul_f32 v[100:101], v[100:101], v[100:101]
	v_and_b32_e32 v5, 0xffff0000, v99
	v_add_f32_e32 v3, v100, v3
	v_add_f32_e32 v3, v101, v3
	v_lshlrev_b32_e32 v101, 16, v98
	v_and_b32_e32 v100, 0xffff0000, v97
	v_pk_mul_f32 v[96:97], v[100:101], v[100:101]
	s_nop 0
	v_add_f32_e32 v3, v96, v3
	v_add_f32_e32 v3, v97, v3
	v_lshlrev_b32_e32 v97, 16, v99
	v_and_b32_e32 v96, 0xffff0000, v98
	v_pk_mul_f32 v[96:97], v[96:97], v[96:97]
	s_nop 0
	v_add_f32_e32 v3, v96, v3
	v_add_f32_e32 v3, v97, v3
	v_fmac_f32_e32 v3, v5, v5
	v_lshlrev_b32_e32 v5, 16, v124
	v_lshlrev_b32_e32 v23, 16, v125
	v_and_b32_e32 v22, 0xffff0000, v124
	v_fmac_f32_e32 v3, v5, v5
	v_pk_mul_f32 v[22:23], v[22:23], v[22:23]
	v_and_b32_e32 v5, 0xffff0000, v127
	v_add_f32_e32 v3, v22, v3
	v_add_f32_e32 v3, v23, v3
	v_lshlrev_b32_e32 v23, 16, v126
	v_and_b32_e32 v22, 0xffff0000, v125
	v_pk_mul_f32 v[124:125], v[22:23], v[22:23]
	s_nop 0
	v_add_f32_e32 v3, v124, v3
	v_add_f32_e32 v3, v125, v3
	v_lshlrev_b32_e32 v125, 16, v127
	v_and_b32_e32 v124, 0xffff0000, v126
	v_pk_mul_f32 v[124:125], v[124:125], v[124:125]
	s_nop 0
	v_add_f32_e32 v3, v124, v3
	v_add_f32_e32 v3, v125, v3
	v_fmac_f32_e32 v3, v5, v5
	v_lshlrev_b32_e32 v5, 16, v120
	v_lshlrev_b32_e32 v125, 16, v121
	v_and_b32_e32 v124, 0xffff0000, v120
	v_fmac_f32_e32 v3, v5, v5
	v_pk_mul_f32 v[124:125], v[124:125], v[124:125]
	v_and_b32_e32 v5, 0xffff0000, v123
	v_add_f32_e32 v3, v124, v3
	v_add_f32_e32 v3, v125, v3
	v_lshlrev_b32_e32 v125, 16, v122
	v_and_b32_e32 v124, 0xffff0000, v121
	v_pk_mul_f32 v[120:121], v[124:125], v[124:125]
	s_nop 0
	v_add_f32_e32 v3, v120, v3
	v_add_f32_e32 v3, v121, v3
	v_lshlrev_b32_e32 v121, 16, v123
	v_and_b32_e32 v120, 0xffff0000, v122
	v_pk_mul_f32 v[120:121], v[120:121], v[120:121]
	s_nop 0
	v_add_f32_e32 v3, v120, v3
	v_add_f32_e32 v3, v121, v3
	v_fmac_f32_e32 v3, v5, v5
	v_lshlrev_b32_e32 v5, 16, v116
	v_lshlrev_b32_e32 v121, 16, v117
	v_and_b32_e32 v120, 0xffff0000, v116
	v_fmac_f32_e32 v3, v5, v5
	v_pk_mul_f32 v[120:121], v[120:121], v[120:121]
	v_and_b32_e32 v5, 0xffff0000, v119
	v_add_f32_e32 v3, v120, v3
	v_add_f32_e32 v3, v121, v3
	v_lshlrev_b32_e32 v121, 16, v118
	v_and_b32_e32 v120, 0xffff0000, v117
	v_pk_mul_f32 v[116:117], v[120:121], v[120:121]
	s_nop 0
	v_add_f32_e32 v3, v116, v3
	v_add_f32_e32 v3, v117, v3
	v_lshlrev_b32_e32 v117, 16, v119
	v_and_b32_e32 v116, 0xffff0000, v118
	v_pk_mul_f32 v[116:117], v[116:117], v[116:117]
	s_nop 0
	v_add_f32_e32 v3, v116, v3
	v_add_f32_e32 v3, v117, v3
	v_fmac_f32_e32 v3, v5, v5
	v_lshlrev_b32_e32 v5, 16, v112
	v_lshlrev_b32_e32 v117, 16, v113
	v_and_b32_e32 v116, 0xffff0000, v112
	v_fmac_f32_e32 v3, v5, v5
	v_pk_mul_f32 v[116:117], v[116:117], v[116:117]
	v_and_b32_e32 v5, 0xffff0000, v115
	v_add_f32_e32 v3, v116, v3
	v_add_f32_e32 v3, v117, v3
	v_lshlrev_b32_e32 v117, 16, v114
	v_and_b32_e32 v116, 0xffff0000, v113
	v_pk_mul_f32 v[112:113], v[116:117], v[116:117]
	s_nop 0
	v_add_f32_e32 v3, v112, v3
	v_add_f32_e32 v3, v113, v3
	v_lshlrev_b32_e32 v113, 16, v115
	v_and_b32_e32 v112, 0xffff0000, v114
	v_pk_mul_f32 v[112:113], v[112:113], v[112:113]
	s_nop 0
	v_add_f32_e32 v3, v112, v3
	v_add_f32_e32 v3, v113, v3
	v_fmac_f32_e32 v3, v5, v5
	ds_bpermute_b32 v0, v4, v3
	s_and_saveexec_b64 s[2:3], s[78:79]
	s_cbranch_execz .LBB0_1186
	s_waitcnt lgkmcnt(0)
	v_add_f32_e32 v0, v3, v0
	s_mov_b32 s6, 0x43c00000
	v_div_scale_f32 v1, s[4:5], s6, s6, v0
	v_rcp_f32_e32 v3, v1
	v_div_scale_f32 v4, vcc, v0, s6, v0
	s_mov_b32 s4, 0x800000
	v_fma_f32 v5, -v1, v3, 1.0
	v_fmac_f32_e32 v3, v5, v3
	v_mul_f32_e32 v5, v4, v3
	v_fma_f32 v6, -v1, v5, v4
	v_fmac_f32_e32 v5, v6, v3
	v_fma_f32 v1, -v1, v5, v4
	v_div_fmas_f32 v1, v1, v3, v5
	v_div_fixup_f32 v0, v1, s6, v0
	v_add_f32_e32 v0, 0x358637bd, v0
	v_mul_f32_e32 v1, 0x4b800000, v0
	v_cmp_gt_f32_e32 vcc, s4, v0
	s_nop 1
	v_cndmask_b32_e32 v0, v0, v1, vcc
	v_rsq_f32_e32 v0, v0
	s_nop 0
	v_mul_f32_e32 v1, 0x45800000, v0
	v_cndmask_b32_e32 v0, v0, v1, vcc
	ds_write_b32 v2, v0 offset:3072
